# K-loop: B0 fragment reads hoisted into the previous MFMA group (+vmcnt(8) guard), group-closing barrier moved up by one MFMA, chain MFMA order
# speedup vs baseline: 1.0287x; 1.0206x over previous
; #define PG8_STAGE(bufoff, gbase, voff) do { _Pragma("unroll") for (int _i = 0; _i < 2; ++_i) \
;         __builtin_amdgcn_global_load_lds((const unsigned*)((const char*)(gbase) + (voff)[_i]), (LAS unsigned*)(lds + (bufoff) + ldsw + _i * 8192), 16, 0, 0); } while (0)
; #define PG8_LDA(dst, b, h) do { _Pragma("unroll") for (int m = 0; m < 4; ++m) _Pragma("unroll") for (int k = 0; k < 2; ++k) dst[m][k] = *(const LAS bf16x8*)(lds + PG8_SA(b, h) + aoff + m * 2048 + k * 1024); } while (0)
; #define PG8_LDB(dst, b, h) do { _Pragma("unroll") for (int n = 0; n < 2; ++n) _Pragma("unroll") for (int k = 0; k < 2; ++k) dst[n][k] = *(const LAS bf16x8*)(lds + PG8_SB(b, h) + boff + n * 2048 + k * 1024); } while (0)
; #define PG8_MMA(ai, bj, At, Bt) do { __builtin_amdgcn_s_setprio(1); _Pragma("unroll") for (int m = 0; m < 4; ++m) _Pragma("unroll") for (int n = 0; n < 2; ++n) _Pragma("unroll") for (int k = 0; k < 2; ++k) \
;         acc[ai][bj][m][n] = __builtin_amdgcn_mfma_f32_16x16x32_bf16(Bt[n][k], At[m][k], acc[ai][bj][m][n], 0, 0, 0); __builtin_amdgcn_s_setprio(0); } while (0)
; #define PG8_WAIT_L(n) asm volatile("s_waitcnt lgkmcnt(" #n ")" ::: "memory")
; template <class Epi, class Sched>
; __device__ __forceinline__ void gemm_phase(LAS unsigned char* lds, const Gemm g, const Sched& S, const Epi& E) {
;     ...
;         const bool has_next = S.next(ui + 1, nxt);
;         const char* nA = has_next ? PG8_APANEL(nxt.pm) : cA; const char* nB = has_next ? (const char*)g.Bt + (size_t)nxt.pn * tstep : cB;
;         for (int t = 0; t < nt; t += 2) {
;             const bool last = (t == nt - 2);
;             const char* a1 = cA + (size_t)(t + 1) * kstep;
;             const char* a2 = last ? nA : cA + (size_t)(t + 2) * kstep; const char* b2 = last ? nB : cB + (size_t)(t + 2) * kstep;
;             const char* a3 = a2 + kstep; const char* b3 = b2 + kstep;
;             PG8_LDB(B0, 0, 0); PG8_SCHED; PG8_LDA(At, 0, 0); PG8_STAGE(PG8_SA(1, 1), a1 + hstep, voffA);
;             PG8_WAIT_L(8); PG8_BAR; PG8_WAIT_L(0); PG8_MMA(0, 0, At, B0); PG8_BAR; PG8_SCHED;
;     ...
; #pragma unroll
;         for (int a = 0; a < 2; ++a)
; #pragma unroll
;             for (int b = 0; b < 2; ++b)
; #pragma unroll
;                 for (int m = 0; m < 4; ++m)
; #pragma unroll
;                     for (int n = 0; n < 2; ++n) acc[a][b][m][n] = (f32x4){0.f, 0.f, 0.f, 0.f};
.LBB0_164:
	s_cmp_lt_i32 s44, 0x100000
	s_cselect_b32 s24, s20, 0xffffff80
	s_cselect_b32 s25, s11, 0
	s_ashr_i32 s45, s44, 31
	s_lshl_b64 s[34:35], s[44:45], 19
	v_cmp_lt_i64_e32 vcc, s[46:47], v[152:153]
	s_add_u32 s46, s25, s34
	s_addc_u32 s47, s24, s35
	s_and_b64 s[34:35], vcc, exec
	s_cselect_b32 s34, s47, s49
	s_cselect_b32 s45, s46, s48
	s_ashr_i32 s43, s42, 31
	s_lshl_b64 s[60:61], s[42:43], 19
	s_add_u32 s76, s16, s60
	s_addc_u32 s77, s92, s61
	s_and_b64 s[60:61], vcc, exec
	s_cselect_b32 s43, s77, s39
	s_cselect_b32 s79, s76, s38
	s_add_u32 vcc_lo, s38, 0x100
	s_addc_u32 s35, s39, 0
	s_add_u32 s38, s48, 0x40080
	v_mov_b32_e32 v2, 0
	s_addc_u32 s39, s49, 0
	s_mov_b32 s50, -2
	v_mov_b32_e32 v3, v2
	v_mov_b32_e32 v4, v2
	v_mov_b32_e32 v5, v2
	v_mov_b32_e32 v6, v2
	v_mov_b32_e32 v7, v2
	v_mov_b32_e32 v8, v2
	v_mov_b32_e32 v9, v2
	v_mov_b32_e32 v18, v2
	v_mov_b32_e32 v19, v2
	v_mov_b32_e32 v20, v2
	v_mov_b32_e32 v21, v2
	v_mov_b32_e32 v22, v2
	v_mov_b32_e32 v23, v2
	v_mov_b32_e32 v24, v2
	v_mov_b32_e32 v25, v2
	v_mov_b32_e32 v34, v2
	v_mov_b32_e32 v35, v2
	v_mov_b32_e32 v36, v2
	v_mov_b32_e32 v37, v2
	v_mov_b32_e32 v38, v2
	v_mov_b32_e32 v39, v2
	v_mov_b32_e32 v40, v2
	v_mov_b32_e32 v41, v2
	v_mov_b32_e32 v50, v2
	v_mov_b32_e32 v51, v2
	v_mov_b32_e32 v52, v2
	v_mov_b32_e32 v53, v2
	v_mov_b32_e32 v54, v2
	v_mov_b32_e32 v55, v2
	v_mov_b32_e32 v56, v2
	v_mov_b32_e32 v57, v2
	v_mov_b32_e32 v10, v2
	v_mov_b32_e32 v11, v2
	v_mov_b32_e32 v12, v2
	v_mov_b32_e32 v13, v2
	v_mov_b32_e32 v14, v2
	v_mov_b32_e32 v15, v2
	v_mov_b32_e32 v16, v2
	v_mov_b32_e32 v17, v2
	v_mov_b32_e32 v26, v2
	v_mov_b32_e32 v27, v2
	v_mov_b32_e32 v28, v2
	v_mov_b32_e32 v29, v2
	v_mov_b32_e32 v30, v2
	v_mov_b32_e32 v31, v2
	v_mov_b32_e32 v32, v2
	v_mov_b32_e32 v33, v2
	v_mov_b32_e32 v42, v2
	v_mov_b32_e32 v43, v2
	v_mov_b32_e32 v44, v2
	v_mov_b32_e32 v45, v2
	v_mov_b32_e32 v46, v2
	v_mov_b32_e32 v47, v2
	v_mov_b32_e32 v48, v2
	v_mov_b32_e32 v49, v2
	v_mov_b32_e32 v58, v2
	v_mov_b32_e32 v59, v2
	v_mov_b32_e32 v60, v2
	v_mov_b32_e32 v61, v2
	v_mov_b32_e32 v62, v2
	v_mov_b32_e32 v63, v2
	v_mov_b32_e32 v64, v2
	v_mov_b32_e32 v65, v2
	v_mov_b32_e32 v66, v2
	v_mov_b32_e32 v67, v2
	v_mov_b32_e32 v68, v2
	v_mov_b32_e32 v69, v2
	v_mov_b32_e32 v70, v2
	v_mov_b32_e32 v71, v2
	v_mov_b32_e32 v72, v2
	v_mov_b32_e32 v73, v2
	v_mov_b32_e32 v82, v2
	v_mov_b32_e32 v83, v2
	v_mov_b32_e32 v84, v2
	v_mov_b32_e32 v85, v2
	v_mov_b32_e32 v86, v2
	v_mov_b32_e32 v87, v2
	v_mov_b32_e32 v88, v2
	v_mov_b32_e32 v89, v2
	v_mov_b32_e32 v98, v2
	v_mov_b32_e32 v99, v2
	v_mov_b32_e32 v100, v2
	v_mov_b32_e32 v101, v2
	v_mov_b32_e32 v102, v2
	v_mov_b32_e32 v103, v2
	v_mov_b32_e32 v104, v2
	v_mov_b32_e32 v105, v2
	v_mov_b32_e32 v114, v2
	v_mov_b32_e32 v115, v2
	v_mov_b32_e32 v116, v2
	v_mov_b32_e32 v117, v2
	v_mov_b32_e32 v118, v2
	v_mov_b32_e32 v119, v2
	v_mov_b32_e32 v120, v2
	v_mov_b32_e32 v121, v2
	v_mov_b32_e32 v74, v2
	v_mov_b32_e32 v75, v2
	v_mov_b32_e32 v76, v2
	v_mov_b32_e32 v77, v2
	v_mov_b32_e32 v78, v2
	v_mov_b32_e32 v79, v2
	v_mov_b32_e32 v80, v2
	v_mov_b32_e32 v81, v2
	v_mov_b32_e32 v90, v2
	v_mov_b32_e32 v91, v2
	v_mov_b32_e32 v92, v2
	v_mov_b32_e32 v93, v2
	v_mov_b32_e32 v94, v2
	v_mov_b32_e32 v95, v2
	v_mov_b32_e32 v96, v2
	v_mov_b32_e32 v97, v2
	v_mov_b32_e32 v106, v2
	v_mov_b32_e32 v107, v2
	v_mov_b32_e32 v108, v2
	v_mov_b32_e32 v109, v2
	v_mov_b32_e32 v110, v2
	v_mov_b32_e32 v111, v2
	v_mov_b32_e32 v112, v2
	v_mov_b32_e32 v113, v2
	v_mov_b32_e32 v122, v2
	v_mov_b32_e32 v123, v2
	v_mov_b32_e32 v124, v2
	v_mov_b32_e32 v125, v2
	v_mov_b32_e32 v126, v2
	v_mov_b32_e32 v127, v2
	v_mov_b32_e32 v128, v2
	v_mov_b32_e32 v129, v2
	v_add_u32_e32 v249, 0x10000, v167
	ds_read_b128 v[142:145], v249
	ds_read_b128 v[162:165], v249 offset:1024
	ds_read_b128 v[182:185], v249 offset:2048
	ds_read_b128 v[186:189], v249 offset:3072
.LBB0_165:
	s_add_u32 s24, s38, 0xfffc0080
	s_addc_u32 s25, s39, -1
	s_add_i32 vcc_hi, 0, 0x10000
	v_add_u32_e32 v166, vcc_hi, v167
	s_cmp_eq_u32 s50, 12
	s_cselect_b32 s61, s34, s25
	s_cselect_b32 s60, s45, s24
	s_cselect_b32 s49, s43, s35
	s_cselect_b32 s48, s79, vcc_lo
	v_lshl_add_u64 v[222:223], s[38:39], 0, v[140:141]
	s_add_i32 m0, s93, 0xc000
	ds_read_b128 v[190:193], v169
	ds_read_b128 v[194:197], v169 offset:1024
	ds_read_b128 v[198:201], v169 offset:2048
	ds_read_b128 v[202:205], v169 offset:3072
	ds_read_b128 v[206:209], v169 offset:4096
	ds_read_b128 v[210:213], v169 offset:5120
	ds_read_b128 v[214:217], v169 offset:6144
	ds_read_b128 v[218:221], v169 offset:7168
	global_load_lds_dwordx4 v[222:223], off
	v_lshl_add_u64 v[222:223], s[38:39], 0, v[138:139]
	s_add_i32 m0, s93, 0xe000
	s_nop 0
	global_load_lds_dwordx4 v[222:223], off
	s_waitcnt lgkmcnt(8)
	s_barrier
	s_waitcnt lgkmcnt(0)
	s_setprio 1
	s_waitcnt lgkmcnt(0)
	v_mfma_f32_16x16x32_bf16 v[126:129], v[142:145], v[190:193], v[126:129]
	v_mfma_f32_16x16x32_bf16 v[126:129], v[162:165], v[194:197], v[126:129]
	v_mfma_f32_16x16x32_bf16 v[122:125], v[182:185], v[190:193], v[122:125]
	v_mfma_f32_16x16x32_bf16 v[122:125], v[186:189], v[194:197], v[122:125]
	v_mfma_f32_16x16x32_bf16 v[110:113], v[142:145], v[198:201], v[110:113]
	v_mfma_f32_16x16x32_bf16 v[110:113], v[162:165], v[202:205], v[110:113]
	v_mfma_f32_16x16x32_bf16 v[106:109], v[182:185], v[198:201], v[106:109]
	v_mfma_f32_16x16x32_bf16 v[106:109], v[186:189], v[202:205], v[106:109]
	v_mfma_f32_16x16x32_bf16 v[94:97], v[142:145], v[206:209], v[94:97]
	v_mfma_f32_16x16x32_bf16 v[94:97], v[162:165], v[210:213], v[94:97]
	v_mfma_f32_16x16x32_bf16 v[90:93], v[182:185], v[206:209], v[90:93]
	v_mfma_f32_16x16x32_bf16 v[90:93], v[186:189], v[210:213], v[90:93]
	v_mfma_f32_16x16x32_bf16 v[78:81], v[142:145], v[214:217], v[78:81]
	v_mfma_f32_16x16x32_bf16 v[78:81], v[162:165], v[218:221], v[78:81]
	v_mfma_f32_16x16x32_bf16 v[74:77], v[182:185], v[214:217], v[74:77]
	s_barrier
; #define PG8_STAGE(bufoff, gbase, voff) do { _Pragma("unroll") for (int _i = 0; _i < 2; ++_i) \
;         __builtin_amdgcn_global_load_lds((const unsigned*)((const char*)(gbase) + (voff)[_i]), (LAS unsigned*)(lds + (bufoff) + ldsw + _i * 8192), 16, 0, 0); } while (0)
; #define PG8_LDA(dst, b, h) do { _Pragma("unroll") for (int m = 0; m < 4; ++m) _Pragma("unroll") for (int k = 0; k < 2; ++k) dst[m][k] = *(const LAS bf16x8*)(lds + PG8_SA(b, h) + aoff + m * 2048 + k * 1024); } while (0)
; #define PG8_LDB(dst, b, h) do { _Pragma("unroll") for (int n = 0; n < 2; ++n) _Pragma("unroll") for (int k = 0; k < 2; ++k) dst[n][k] = *(const LAS bf16x8*)(lds + PG8_SB(b, h) + boff + n * 2048 + k * 1024); } while (0)
; #define PG8_MMA(ai, bj, At, Bt) do { __builtin_amdgcn_s_setprio(1); _Pragma("unroll") for (int m = 0; m < 4; ++m) _Pragma("unroll") for (int n = 0; n < 2; ++n) _Pragma("unroll") for (int k = 0; k < 2; ++k) \
;         acc[ai][bj][m][n] = __builtin_amdgcn_mfma_f32_16x16x32_bf16(Bt[n][k], At[m][k], acc[ai][bj][m][n], 0, 0, 0); __builtin_amdgcn_s_setprio(0); } while (0)
; #define PG8_WAIT_V(n) asm volatile("s_waitcnt vmcnt(" #n ")" ::: "memory")
; #define PG8_WAIT_L(n) asm volatile("s_waitcnt lgkmcnt(" #n ")" ::: "memory")
; #define PG8_BAR __builtin_amdgcn_s_barrier()
; #define PG8_SCHED __builtin_amdgcn_sched_barrier(0)
; template <class Epi, class Sched>
; __device__ __forceinline__ void gemm_phase(LAS unsigned char* lds, const Gemm g, const Sched& S, const Epi& E) {
;     ...
;             PG8_WAIT_L(8); PG8_BAR; PG8_WAIT_L(0); PG8_MMA(0, 0, At, B0); PG8_BAR; PG8_SCHED;
;             PG8_LDB(B1, 0, 1); PG8_STAGE(PG8_SB(0, 0), b2, voffB);
;             PG8_BAR; PG8_WAIT_L(0); PG8_MMA(0, 1, At, B1); PG8_BAR;
;             PG8_LDA(At, 0, 1); PG8_STAGE(PG8_SA(0, 0), a2, voffA);
;             PG8_BAR; PG8_WAIT_L(0); PG8_MMA(1, 0, At, B0); PG8_BAR; PG8_SCHED;
;             PG8_STAGE(PG8_SB(0, 1), b2 + hstep, voffB);
;             PG8_WAIT_V(6); PG8_BAR; PG8_MMA(1, 1, At, B1); PG8_BAR;
;             PG8_LDB(B0, 1, 0); PG8_SCHED; PG8_LDA(At, 1, 0); PG8_STAGE(PG8_SA(0, 1), a2 + hstep, voffA);
;             PG8_WAIT_L(8); PG8_BAR; PG8_WAIT_L(0); PG8_MMA(0, 0, At, B0); PG8_BAR; PG8_SCHED;
	v_mfma_f32_16x16x32_bf16 v[74:77], v[186:189], v[218:221], v[74:77]
	s_setprio 0
	s_add_i32 s51, 0, 0x14000
	s_add_i32 s24, vcc_hi, s86
	v_add_u32_e32 v166, s51, v167
	v_lshl_add_u64 v[238:239], s[48:49], 0, v[134:135]
	s_mov_b32 m0, s24
	ds_read_b128 v[222:225], v166
	ds_read_b128 v[226:229], v166 offset:1024
	ds_read_b128 v[230:233], v166 offset:2048
	ds_read_b128 v[234:237], v166 offset:3072
	global_load_lds_dwordx4 v[238:239], off
	v_lshl_add_u64 v[240:241], s[48:49], 0, v[130:131]
	s_add_i32 m0, s24, 0x2000
	s_nop 0
	global_load_lds_dwordx4 v[240:241], off
	s_barrier
	s_waitcnt lgkmcnt(0)
	s_setprio 1
	s_waitcnt lgkmcnt(0)
	v_mfma_f32_16x16x32_bf16 v[118:121], v[222:225], v[190:193], v[118:121]
	v_mfma_f32_16x16x32_bf16 v[118:121], v[226:229], v[194:197], v[118:121]
	v_mfma_f32_16x16x32_bf16 v[114:117], v[230:233], v[190:193], v[114:117]
	v_mfma_f32_16x16x32_bf16 v[114:117], v[234:237], v[194:197], v[114:117]
	v_mfma_f32_16x16x32_bf16 v[102:105], v[222:225], v[198:201], v[102:105]
	v_mfma_f32_16x16x32_bf16 v[102:105], v[226:229], v[202:205], v[102:105]
	v_mfma_f32_16x16x32_bf16 v[98:101], v[230:233], v[198:201], v[98:101]
	v_mfma_f32_16x16x32_bf16 v[98:101], v[234:237], v[202:205], v[98:101]
	v_mfma_f32_16x16x32_bf16 v[86:89], v[222:225], v[206:209], v[86:89]
	v_mfma_f32_16x16x32_bf16 v[86:89], v[226:229], v[210:213], v[86:89]
	v_mfma_f32_16x16x32_bf16 v[82:85], v[230:233], v[206:209], v[82:85]
	v_mfma_f32_16x16x32_bf16 v[82:85], v[234:237], v[210:213], v[82:85]
	v_mfma_f32_16x16x32_bf16 v[70:73], v[222:225], v[214:217], v[70:73]
	v_mfma_f32_16x16x32_bf16 v[70:73], v[226:229], v[218:221], v[70:73]
	v_mfma_f32_16x16x32_bf16 v[66:69], v[230:233], v[214:217], v[66:69]
	s_barrier
	v_mfma_f32_16x16x32_bf16 v[66:69], v[234:237], v[218:221], v[66:69]
	s_setprio 0
	s_mov_b32 m0, s93
	v_lshl_add_u64 v[242:243], s[60:61], 0, v[136:137]
	ds_read_b128 v[190:193], v169 offset:16384
	ds_read_b128 v[194:197], v169 offset:17408
	ds_read_b128 v[198:201], v169 offset:18432
	ds_read_b128 v[202:205], v169 offset:19456
	ds_read_b128 v[206:209], v169 offset:20480
	ds_read_b128 v[210:213], v169 offset:21504
	ds_read_b128 v[214:217], v169 offset:22528
	ds_read_b128 v[218:221], v169 offset:23552
	global_load_lds_dwordx4 v[242:243], off
	v_lshl_add_u64 v[244:245], s[60:61], 0, v[132:133]
	s_mov_b32 m0, s98
	s_nop 0
	global_load_lds_dwordx4 v[244:245], off
	s_waitcnt vmcnt(8)
	s_barrier
	s_waitcnt lgkmcnt(0)
	s_setprio 1
	s_waitcnt lgkmcnt(0)
	v_mfma_f32_16x16x32_bf16 v[62:65], v[142:145], v[190:193], v[62:65]
	v_mfma_f32_16x16x32_bf16 v[62:65], v[162:165], v[194:197], v[62:65]
	v_mfma_f32_16x16x32_bf16 v[58:61], v[182:185], v[190:193], v[58:61]
	v_mfma_f32_16x16x32_bf16 v[58:61], v[186:189], v[194:197], v[58:61]
	v_mfma_f32_16x16x32_bf16 v[46:49], v[142:145], v[198:201], v[46:49]
	v_mfma_f32_16x16x32_bf16 v[46:49], v[162:165], v[202:205], v[46:49]
	v_mfma_f32_16x16x32_bf16 v[42:45], v[182:185], v[198:201], v[42:45]
	v_mfma_f32_16x16x32_bf16 v[42:45], v[186:189], v[202:205], v[42:45]
	v_mfma_f32_16x16x32_bf16 v[30:33], v[142:145], v[206:209], v[30:33]
	v_mfma_f32_16x16x32_bf16 v[30:33], v[162:165], v[210:213], v[30:33]
	v_mfma_f32_16x16x32_bf16 v[26:29], v[182:185], v[206:209], v[26:29]
	v_mfma_f32_16x16x32_bf16 v[26:29], v[186:189], v[210:213], v[26:29]
	v_mfma_f32_16x16x32_bf16 v[14:17], v[142:145], v[214:217], v[14:17]
	v_mfma_f32_16x16x32_bf16 v[14:17], v[162:165], v[218:221], v[14:17]
	v_mfma_f32_16x16x32_bf16 v[10:13], v[182:185], v[214:217], v[10:13]
	s_barrier
	v_mfma_f32_16x16x32_bf16 v[10:13], v[186:189], v[218:221], v[10:13]
	s_setprio 0
	s_add_u32 s24, s48, 0x40000
	s_addc_u32 s25, s49, 0
	s_add_i32 s51, s51, s86
	v_lshl_add_u64 v[142:143], s[24:25], 0, v[134:135]
	s_mov_b32 m0, s51
	s_nop 0
	global_load_lds_dwordx4 v[142:143], off
	v_lshl_add_u64 v[142:143], s[24:25], 0, v[130:131]
	s_add_i32 m0, s51, 0x2000
	s_nop 0
	global_load_lds_dwordx4 v[142:143], off
	s_waitcnt vmcnt(6)
	s_barrier
	s_setprio 1
	v_add_u32_e32 v249, 0x18000, v167
	v_mfma_f32_16x16x32_bf16 v[54:57], v[222:225], v[190:193], v[54:57]
	v_mfma_f32_16x16x32_bf16 v[54:57], v[226:229], v[194:197], v[54:57]
	ds_read_b128 v[142:145], v249
	v_mfma_f32_16x16x32_bf16 v[50:53], v[230:233], v[190:193], v[50:53]
	v_mfma_f32_16x16x32_bf16 v[50:53], v[234:237], v[194:197], v[50:53]
	v_mfma_f32_16x16x32_bf16 v[38:41], v[222:225], v[198:201], v[38:41]
	v_mfma_f32_16x16x32_bf16 v[38:41], v[226:229], v[202:205], v[38:41]
	ds_read_b128 v[162:165], v249 offset:1024
	v_mfma_f32_16x16x32_bf16 v[34:37], v[230:233], v[198:201], v[34:37]
	v_mfma_f32_16x16x32_bf16 v[34:37], v[234:237], v[202:205], v[34:37]
	v_mfma_f32_16x16x32_bf16 v[22:25], v[222:225], v[206:209], v[22:25]
	v_mfma_f32_16x16x32_bf16 v[22:25], v[226:229], v[210:213], v[22:25]
	ds_read_b128 v[182:185], v249 offset:2048
	v_mfma_f32_16x16x32_bf16 v[18:21], v[230:233], v[206:209], v[18:21]
	v_mfma_f32_16x16x32_bf16 v[18:21], v[234:237], v[210:213], v[18:21]
	v_mfma_f32_16x16x32_bf16 v[6:9], v[222:225], v[214:217], v[6:9]
	v_mfma_f32_16x16x32_bf16 v[6:9], v[226:229], v[218:221], v[6:9]
	ds_read_b128 v[186:189], v249 offset:3072
	v_mfma_f32_16x16x32_bf16 v[2:5], v[230:233], v[214:217], v[2:5]
	s_barrier
	v_mfma_f32_16x16x32_bf16 v[2:5], v[234:237], v[218:221], v[2:5]
	s_setprio 0
	s_add_i32 s51, 0, 0x18000
	v_add_u32_e32 v166, s51, v167
	s_add_u32 s24, s60, 0x40000
	s_addc_u32 s25, s61, 0
	s_mov_b32 m0, s99
	v_lshl_add_u64 v[222:223], s[24:25], 0, v[136:137]
	ds_read_b128 v[190:193], v169 offset:32768
	ds_read_b128 v[194:197], v169 offset:33792
	ds_read_b128 v[198:201], v169 offset:34816
	ds_read_b128 v[202:205], v169 offset:35840
	ds_read_b128 v[206:209], v169 offset:36864
	ds_read_b128 v[210:213], v169 offset:37888
	ds_read_b128 v[214:217], v169 offset:38912
	ds_read_b128 v[218:221], v169 offset:39936
	global_load_lds_dwordx4 v[222:223], off
	v_lshl_add_u64 v[222:223], s[24:25], 0, v[132:133]
	s_mov_b32 m0, s94
	s_nop 0
	global_load_lds_dwordx4 v[222:223], off
	s_waitcnt lgkmcnt(8)
	s_barrier
; #define PG8_STAGE(bufoff, gbase, voff) do { _Pragma("unroll") for (int _i = 0; _i < 2; ++_i) \
;         __builtin_amdgcn_global_load_lds((const unsigned*)((const char*)(gbase) + (voff)[_i]), (LAS unsigned*)(lds + (bufoff) + ldsw + _i * 8192), 16, 0, 0); } while (0)
; #define PG8_LDA(dst, b, h) do { _Pragma("unroll") for (int m = 0; m < 4; ++m) _Pragma("unroll") for (int k = 0; k < 2; ++k) dst[m][k] = *(const LAS bf16x8*)(lds + PG8_SA(b, h) + aoff + m * 2048 + k * 1024); } while (0)
; #define PG8_LDB(dst, b, h) do { _Pragma("unroll") for (int n = 0; n < 2; ++n) _Pragma("unroll") for (int k = 0; k < 2; ++k) dst[n][k] = *(const LAS bf16x8*)(lds + PG8_SB(b, h) + boff + n * 2048 + k * 1024); } while (0)
; #define PG8_MMA(ai, bj, At, Bt) do { __builtin_amdgcn_s_setprio(1); _Pragma("unroll") for (int m = 0; m < 4; ++m) _Pragma("unroll") for (int n = 0; n < 2; ++n) _Pragma("unroll") for (int k = 0; k < 2; ++k) \
;         acc[ai][bj][m][n] = __builtin_amdgcn_mfma_f32_16x16x32_bf16(Bt[n][k], At[m][k], acc[ai][bj][m][n], 0, 0, 0); __builtin_amdgcn_s_setprio(0); } while (0)
; #define PG8_WAIT_V(n) asm volatile("s_waitcnt vmcnt(" #n ")" ::: "memory")
; #define PG8_WAIT_L(n) asm volatile("s_waitcnt lgkmcnt(" #n ")" ::: "memory")
; #define PG8_BAR __builtin_amdgcn_s_barrier()
; #define PG8_SCHED __builtin_amdgcn_sched_barrier(0)
; template <class Epi, class Sched>
; __device__ __forceinline__ void gemm_phase(LAS unsigned char* lds, const Gemm g, const Sched& S, const Epi& E) {
;     ...
;             PG8_WAIT_L(8); PG8_BAR; PG8_WAIT_L(0); PG8_MMA(0, 0, At, B0); PG8_BAR; PG8_SCHED;
;             PG8_LDB(B1, 1, 1); PG8_STAGE(PG8_SB(1, 0), b3, voffB);
;             PG8_BAR; PG8_WAIT_L(0); PG8_MMA(0, 1, At, B1); PG8_BAR;
;             PG8_LDA(At, 1, 1); PG8_STAGE(PG8_SA(1, 0), a3, voffA);
;             PG8_BAR; PG8_WAIT_L(0); PG8_MMA(1, 0, At, B0); PG8_BAR; PG8_SCHED;
;             PG8_STAGE(PG8_SB(1, 1), b3 + hstep, voffB);
;             PG8_WAIT_V(6); PG8_BAR; PG8_MMA(1, 1, At, B1); PG8_BAR;
;         }
;         if (wr == 0) PG8_BAR;
	s_waitcnt lgkmcnt(0)
	s_setprio 1
	s_waitcnt lgkmcnt(0)
	v_mfma_f32_16x16x32_bf16 v[126:129], v[142:145], v[190:193], v[126:129]
	v_mfma_f32_16x16x32_bf16 v[126:129], v[162:165], v[194:197], v[126:129]
	v_mfma_f32_16x16x32_bf16 v[122:125], v[182:185], v[190:193], v[122:125]
	v_mfma_f32_16x16x32_bf16 v[122:125], v[186:189], v[194:197], v[122:125]
	v_mfma_f32_16x16x32_bf16 v[110:113], v[142:145], v[198:201], v[110:113]
	v_mfma_f32_16x16x32_bf16 v[110:113], v[162:165], v[202:205], v[110:113]
	v_mfma_f32_16x16x32_bf16 v[106:109], v[182:185], v[198:201], v[106:109]
	v_mfma_f32_16x16x32_bf16 v[106:109], v[186:189], v[202:205], v[106:109]
	v_mfma_f32_16x16x32_bf16 v[94:97], v[142:145], v[206:209], v[94:97]
	v_mfma_f32_16x16x32_bf16 v[94:97], v[162:165], v[210:213], v[94:97]
	v_mfma_f32_16x16x32_bf16 v[90:93], v[182:185], v[206:209], v[90:93]
	v_mfma_f32_16x16x32_bf16 v[90:93], v[186:189], v[210:213], v[90:93]
	v_mfma_f32_16x16x32_bf16 v[78:81], v[142:145], v[214:217], v[78:81]
	v_mfma_f32_16x16x32_bf16 v[78:81], v[162:165], v[218:221], v[78:81]
	v_mfma_f32_16x16x32_bf16 v[74:77], v[182:185], v[214:217], v[74:77]
	s_barrier
	v_mfma_f32_16x16x32_bf16 v[74:77], v[186:189], v[218:221], v[74:77]
	s_setprio 0
	s_add_i32 s60, 0, 0x1c000
	s_add_i32 s24, s51, s86
	v_add_u32_e32 v166, s60, v167
	v_lshl_add_u64 v[238:239], v[238:239], 0, s[12:13]
	s_mov_b32 m0, s24
	ds_read_b128 v[222:225], v166
	ds_read_b128 v[226:229], v166 offset:1024
	ds_read_b128 v[230:233], v166 offset:2048
	ds_read_b128 v[234:237], v166 offset:3072
	global_load_lds_dwordx4 v[238:239], off
	v_lshl_add_u64 v[238:239], v[240:241], 0, s[12:13]
	s_add_i32 m0, s24, 0x2000
	s_nop 0
	global_load_lds_dwordx4 v[238:239], off
	s_barrier
	s_waitcnt lgkmcnt(0)
	s_setprio 1
	s_waitcnt lgkmcnt(0)
	v_mfma_f32_16x16x32_bf16 v[118:121], v[222:225], v[190:193], v[118:121]
	v_mfma_f32_16x16x32_bf16 v[118:121], v[226:229], v[194:197], v[118:121]
	v_mfma_f32_16x16x32_bf16 v[114:117], v[230:233], v[190:193], v[114:117]
	v_mfma_f32_16x16x32_bf16 v[114:117], v[234:237], v[194:197], v[114:117]
	v_mfma_f32_16x16x32_bf16 v[102:105], v[222:225], v[198:201], v[102:105]
	v_mfma_f32_16x16x32_bf16 v[102:105], v[226:229], v[202:205], v[102:105]
	v_mfma_f32_16x16x32_bf16 v[98:101], v[230:233], v[198:201], v[98:101]
	v_mfma_f32_16x16x32_bf16 v[98:101], v[234:237], v[202:205], v[98:101]
	v_mfma_f32_16x16x32_bf16 v[86:89], v[222:225], v[206:209], v[86:89]
	v_mfma_f32_16x16x32_bf16 v[86:89], v[226:229], v[210:213], v[86:89]
	v_mfma_f32_16x16x32_bf16 v[82:85], v[230:233], v[206:209], v[82:85]
	v_mfma_f32_16x16x32_bf16 v[82:85], v[234:237], v[210:213], v[82:85]
	v_mfma_f32_16x16x32_bf16 v[70:73], v[222:225], v[214:217], v[70:73]
	v_mfma_f32_16x16x32_bf16 v[70:73], v[226:229], v[218:221], v[70:73]
	v_mfma_f32_16x16x32_bf16 v[66:69], v[230:233], v[214:217], v[66:69]
	s_barrier
	v_mfma_f32_16x16x32_bf16 v[66:69], v[234:237], v[218:221], v[66:69]
	s_setprio 0
	s_mov_b32 m0, s95
	v_lshl_add_u64 v[238:239], v[242:243], 0, s[12:13]
	ds_read_b128 v[190:193], v169 offset:49152
	ds_read_b128 v[194:197], v169 offset:50176
	ds_read_b128 v[198:201], v169 offset:51200
	ds_read_b128 v[202:205], v169 offset:52224
	ds_read_b128 v[206:209], v169 offset:53248
	ds_read_b128 v[210:213], v169 offset:54272
	ds_read_b128 v[214:217], v169 offset:55296
	ds_read_b128 v[218:221], v169 offset:56320
	global_load_lds_dwordx4 v[238:239], off
	v_lshl_add_u64 v[238:239], v[244:245], 0, s[12:13]
	s_mov_b32 m0, s96
	s_nop 0
	global_load_lds_dwordx4 v[238:239], off
	s_waitcnt vmcnt(8)
	s_barrier
	s_waitcnt lgkmcnt(0)
	s_setprio 1
	s_waitcnt lgkmcnt(0)
	v_mfma_f32_16x16x32_bf16 v[62:65], v[142:145], v[190:193], v[62:65]
	v_mfma_f32_16x16x32_bf16 v[62:65], v[162:165], v[194:197], v[62:65]
	v_mfma_f32_16x16x32_bf16 v[58:61], v[182:185], v[190:193], v[58:61]
	v_mfma_f32_16x16x32_bf16 v[58:61], v[186:189], v[194:197], v[58:61]
	v_mfma_f32_16x16x32_bf16 v[46:49], v[142:145], v[198:201], v[46:49]
	v_mfma_f32_16x16x32_bf16 v[46:49], v[162:165], v[202:205], v[46:49]
	v_mfma_f32_16x16x32_bf16 v[42:45], v[182:185], v[198:201], v[42:45]
	v_mfma_f32_16x16x32_bf16 v[42:45], v[186:189], v[202:205], v[42:45]
	v_mfma_f32_16x16x32_bf16 v[30:33], v[142:145], v[206:209], v[30:33]
	v_mfma_f32_16x16x32_bf16 v[30:33], v[162:165], v[210:213], v[30:33]
	v_mfma_f32_16x16x32_bf16 v[26:29], v[182:185], v[206:209], v[26:29]
	v_mfma_f32_16x16x32_bf16 v[26:29], v[186:189], v[210:213], v[26:29]
	v_mfma_f32_16x16x32_bf16 v[14:17], v[142:145], v[214:217], v[14:17]
	v_mfma_f32_16x16x32_bf16 v[14:17], v[162:165], v[218:221], v[14:17]
	v_mfma_f32_16x16x32_bf16 v[10:13], v[182:185], v[214:217], v[10:13]
	s_barrier
	v_mfma_f32_16x16x32_bf16 v[10:13], v[186:189], v[218:221], v[10:13]
	s_setprio 0
	s_add_u32 s24, s48, 0x40080
	s_addc_u32 s25, s49, 0
	s_add_i32 s48, s60, s86
	v_lshl_add_u64 v[142:143], s[24:25], 0, v[134:135]
	s_mov_b32 m0, s48
	s_nop 0
	global_load_lds_dwordx4 v[142:143], off
	v_lshl_add_u64 v[142:143], s[24:25], 0, v[130:131]
	s_add_i32 m0, s48, 0x2000
	s_nop 0
	global_load_lds_dwordx4 v[142:143], off
	s_waitcnt vmcnt(6)
	s_barrier
	s_setprio 1
	v_add_u32_e32 v249, 0x10000, v167
	v_mfma_f32_16x16x32_bf16 v[54:57], v[222:225], v[190:193], v[54:57]
	v_mfma_f32_16x16x32_bf16 v[54:57], v[226:229], v[194:197], v[54:57]
	ds_read_b128 v[142:145], v249
	v_mfma_f32_16x16x32_bf16 v[50:53], v[230:233], v[190:193], v[50:53]
	v_mfma_f32_16x16x32_bf16 v[50:53], v[234:237], v[194:197], v[50:53]
	v_mfma_f32_16x16x32_bf16 v[38:41], v[222:225], v[198:201], v[38:41]
	v_mfma_f32_16x16x32_bf16 v[38:41], v[226:229], v[202:205], v[38:41]
	ds_read_b128 v[162:165], v249 offset:1024
	v_mfma_f32_16x16x32_bf16 v[34:37], v[230:233], v[198:201], v[34:37]
	v_mfma_f32_16x16x32_bf16 v[34:37], v[234:237], v[202:205], v[34:37]
	v_mfma_f32_16x16x32_bf16 v[22:25], v[222:225], v[206:209], v[22:25]
	v_mfma_f32_16x16x32_bf16 v[22:25], v[226:229], v[210:213], v[22:25]
	ds_read_b128 v[182:185], v249 offset:2048
	v_mfma_f32_16x16x32_bf16 v[18:21], v[230:233], v[206:209], v[18:21]
	v_mfma_f32_16x16x32_bf16 v[18:21], v[234:237], v[210:213], v[18:21]
	v_mfma_f32_16x16x32_bf16 v[6:9], v[222:225], v[214:217], v[6:9]
	v_mfma_f32_16x16x32_bf16 v[6:9], v[226:229], v[218:221], v[6:9]
	ds_read_b128 v[186:189], v249 offset:3072
	v_mfma_f32_16x16x32_bf16 v[2:5], v[230:233], v[214:217], v[2:5]
	s_barrier
	v_mfma_f32_16x16x32_bf16 v[2:5], v[234:237], v[218:221], v[2:5]
	s_setprio 0
	s_add_i32 s50, s50, 2
	s_add_u32 vcc_lo, vcc_lo, 0x100
	s_addc_u32 s35, s35, 0
	s_add_u32 s38, s38, 0x100
	s_addc_u32 s39, s39, 0
	s_cmp_gt_u32 s50, 13
	s_cbranch_scc0 .LBB0_165
	s_waitcnt lgkmcnt(0)
	s_and_b64 vcc, exec, s[40:41]
	s_cbranch_vccz .LBB0_168
	s_barrier

; #define PG8_STAGE(bufoff, gbase, voff) do { _Pragma("unroll") for (int _i = 0; _i < 2; ++_i) \
;         __builtin_amdgcn_global_load_lds((const unsigned*)((const char*)(gbase) + (voff)[_i]), (LAS unsigned*)(lds + (bufoff) + ldsw + _i * 8192), 16, 0, 0); } while (0)
; #define PG8_LDA(dst, b, h) do { _Pragma("unroll") for (int m = 0; m < 4; ++m) _Pragma("unroll") for (int k = 0; k < 2; ++k) dst[m][k] = *(const LAS bf16x8*)(lds + PG8_SA(b, h) + aoff + m * 2048 + k * 1024); } while (0)
; #define PG8_LDB(dst, b, h) do { _Pragma("unroll") for (int n = 0; n < 2; ++n) _Pragma("unroll") for (int k = 0; k < 2; ++k) dst[n][k] = *(const LAS bf16x8*)(lds + PG8_SB(b, h) + boff + n * 2048 + k * 1024); } while (0)
; #define PG8_MMA(ai, bj, At, Bt) do { __builtin_amdgcn_s_setprio(1); _Pragma("unroll") for (int m = 0; m < 4; ++m) _Pragma("unroll") for (int n = 0; n < 2; ++n) _Pragma("unroll") for (int k = 0; k < 2; ++k) \
;         acc[ai][bj][m][n] = __builtin_amdgcn_mfma_f32_16x16x32_bf16(Bt[n][k], At[m][k], acc[ai][bj][m][n], 0, 0, 0); __builtin_amdgcn_s_setprio(0); } while (0)
; #define PG8_WAIT_L(n) asm volatile("s_waitcnt lgkmcnt(" #n ")" ::: "memory")
; template <class Epi, class Sched>
; __device__ __forceinline__ void gemm_phase(LAS unsigned char* lds, const Gemm g, const Sched& S, const Epi& E) {
;     ...
;         const bool has_next = S.next(ui + 1, nxt);
;         const char* nA = has_next ? PG8_APANEL(nxt.pm) : cA; const char* nB = has_next ? (const char*)g.Bt + (size_t)nxt.pn * tstep : cB;
;         for (int t = 0; t < nt; t += 2) {
;             const bool last = (t == nt - 2);
;             const char* a1 = cA + (size_t)(t + 1) * kstep;
;             const char* a2 = last ? nA : cA + (size_t)(t + 2) * kstep; const char* b2 = last ? nB : cB + (size_t)(t + 2) * kstep;
;             const char* a3 = a2 + kstep; const char* b3 = b2 + kstep;
;             PG8_LDB(B0, 0, 0); PG8_SCHED; PG8_LDA(At, 0, 0); PG8_STAGE(PG8_SA(1, 1), a1 + hstep, voffA);
;             PG8_WAIT_L(8); PG8_BAR; PG8_WAIT_L(0); PG8_MMA(0, 0, At, B0); PG8_BAR; PG8_SCHED;
;     ...
; #pragma unroll
;         for (int a = 0; a < 2; ++a)
; #pragma unroll
;             for (int b = 0; b < 2; ++b)
; #pragma unroll
;                 for (int m = 0; m < 4; ++m)
; #pragma unroll
;                     for (int n = 0; n < 2; ++n) acc[a][b][m][n] = (f32x4){0.f, 0.f, 0.f, 0.f};
.LBB0_415:
	s_ashr_i32 s47, s46, 31
	s_lshl_b64 s[24:25], s[46:47], 19
	s_add_u32 s48, s82, s24
	s_addc_u32 s49, s83, s25
	s_and_b64 s[0:1], s[0:1], exec
	s_cselect_b32 s47, s49, s37
	s_cselect_b32 s61, s48, s36
	s_add_u32 s35, s36, 0x100
	s_addc_u32 s50, s37, 0
	s_add_u32 s0, s38, 0x40080
	v_mov_b32_e32 v2, 0
	s_addc_u32 s1, s39, 0
	s_mov_b32 s38, -2
	v_mov_b32_e32 v3, v2
	v_mov_b32_e32 v4, v2
	v_mov_b32_e32 v5, v2
	v_mov_b32_e32 v6, v2
	v_mov_b32_e32 v7, v2
	v_mov_b32_e32 v8, v2
	v_mov_b32_e32 v9, v2
	v_mov_b32_e32 v10, v2
	v_mov_b32_e32 v11, v2
	v_mov_b32_e32 v12, v2
	v_mov_b32_e32 v13, v2
	v_mov_b32_e32 v18, v2
	v_mov_b32_e32 v19, v2
	v_mov_b32_e32 v20, v2
	v_mov_b32_e32 v21, v2
	v_mov_b32_e32 v26, v2
	v_mov_b32_e32 v27, v2
	v_mov_b32_e32 v28, v2
	v_mov_b32_e32 v29, v2
	v_mov_b32_e32 v34, v2
	v_mov_b32_e32 v35, v2
	v_mov_b32_e32 v36, v2
	v_mov_b32_e32 v37, v2
	v_mov_b32_e32 v42, v2
	v_mov_b32_e32 v43, v2
	v_mov_b32_e32 v44, v2
	v_mov_b32_e32 v45, v2
	v_mov_b32_e32 v50, v2
	v_mov_b32_e32 v51, v2
	v_mov_b32_e32 v52, v2
	v_mov_b32_e32 v53, v2
	v_mov_b32_e32 v14, v2
	v_mov_b32_e32 v15, v2
	v_mov_b32_e32 v16, v2
	v_mov_b32_e32 v17, v2
	v_mov_b32_e32 v22, v2
	v_mov_b32_e32 v23, v2
	v_mov_b32_e32 v24, v2
	v_mov_b32_e32 v25, v2
	v_mov_b32_e32 v30, v2
	v_mov_b32_e32 v31, v2
	v_mov_b32_e32 v32, v2
	v_mov_b32_e32 v33, v2
	v_mov_b32_e32 v38, v2
	v_mov_b32_e32 v39, v2
	v_mov_b32_e32 v40, v2
	v_mov_b32_e32 v41, v2
	v_mov_b32_e32 v46, v2
	v_mov_b32_e32 v47, v2
	v_mov_b32_e32 v48, v2
	v_mov_b32_e32 v49, v2
	v_mov_b32_e32 v54, v2
	v_mov_b32_e32 v55, v2
	v_mov_b32_e32 v56, v2
	v_mov_b32_e32 v57, v2
	v_mov_b32_e32 v58, v2
	v_mov_b32_e32 v59, v2
	v_mov_b32_e32 v60, v2
	v_mov_b32_e32 v61, v2
	v_mov_b32_e32 v62, v2
	v_mov_b32_e32 v63, v2
	v_mov_b32_e32 v64, v2
	v_mov_b32_e32 v65, v2
	v_mov_b32_e32 v66, v2
	v_mov_b32_e32 v67, v2
	v_mov_b32_e32 v68, v2
	v_mov_b32_e32 v69, v2
	v_mov_b32_e32 v70, v2
	v_mov_b32_e32 v71, v2
	v_mov_b32_e32 v72, v2
	v_mov_b32_e32 v73, v2
	v_mov_b32_e32 v74, v2
	v_mov_b32_e32 v75, v2
	v_mov_b32_e32 v76, v2
	v_mov_b32_e32 v77, v2
	v_mov_b32_e32 v82, v2
	v_mov_b32_e32 v83, v2
	v_mov_b32_e32 v84, v2
	v_mov_b32_e32 v85, v2
	v_mov_b32_e32 v90, v2
	v_mov_b32_e32 v91, v2
	v_mov_b32_e32 v92, v2
	v_mov_b32_e32 v93, v2
	v_mov_b32_e32 v98, v2
	v_mov_b32_e32 v99, v2
	v_mov_b32_e32 v100, v2
	v_mov_b32_e32 v101, v2
	v_mov_b32_e32 v106, v2
	v_mov_b32_e32 v107, v2
	v_mov_b32_e32 v108, v2
	v_mov_b32_e32 v109, v2
	v_mov_b32_e32 v114, v2
	v_mov_b32_e32 v115, v2
	v_mov_b32_e32 v116, v2
	v_mov_b32_e32 v117, v2
	v_mov_b32_e32 v78, v2
	v_mov_b32_e32 v79, v2
	v_mov_b32_e32 v80, v2
	v_mov_b32_e32 v81, v2
	v_mov_b32_e32 v86, v2
	v_mov_b32_e32 v87, v2
	v_mov_b32_e32 v88, v2
	v_mov_b32_e32 v89, v2
	v_mov_b32_e32 v94, v2
	v_mov_b32_e32 v95, v2
	v_mov_b32_e32 v96, v2
	v_mov_b32_e32 v97, v2
	v_mov_b32_e32 v102, v2
	v_mov_b32_e32 v103, v2
	v_mov_b32_e32 v104, v2
	v_mov_b32_e32 v105, v2
	v_mov_b32_e32 v110, v2
	v_mov_b32_e32 v111, v2
	v_mov_b32_e32 v112, v2
	v_mov_b32_e32 v113, v2
	v_mov_b32_e32 v118, v2
	v_mov_b32_e32 v119, v2
	v_mov_b32_e32 v120, v2
	v_mov_b32_e32 v121, v2
	v_mov_b32_e32 v122, v2
	v_mov_b32_e32 v123, v2
	v_mov_b32_e32 v124, v2
	v_mov_b32_e32 v125, v2
	v_mov_b32_e32 v126, v2
	v_mov_b32_e32 v127, v2
	v_mov_b32_e32 v128, v2
	v_mov_b32_e32 v129, v2
	v_add_u32_e32 v249, 0x10000, v144
	ds_read_b128 v[164:167], v249
	ds_read_b128 v[182:185], v249 offset:1024
	ds_read_b128 v[186:189], v249 offset:2048
	ds_read_b128 v[190:193], v249 offset:3072
.LBB0_416:
	s_add_u32 s24, s0, 0xfffc0080
	s_addc_u32 s25, s1, -1
	s_add_i32 s39, 0, 0x10000
	v_add_u32_e32 v142, s39, v144
	s_cmp_eq_u32 s38, 12
	s_cselect_b32 vcc_hi, s77, s25
	s_cselect_b32 vcc_lo, s76, s24
	s_cselect_b32 s37, s47, s50
	s_cselect_b32 s36, s61, s35
	v_lshl_add_u64 v[142:143], s[0:1], 0, v[140:141]
	s_add_i32 m0, s93, 0xc000
	ds_read_b128 v[194:197], v162
	ds_read_b128 v[198:201], v162 offset:1024
	ds_read_b128 v[202:205], v162 offset:2048
	ds_read_b128 v[206:209], v162 offset:3072
	ds_read_b128 v[210:213], v162 offset:4096
	ds_read_b128 v[214:217], v162 offset:5120
	ds_read_b128 v[218:221], v162 offset:6144
	ds_read_b128 v[222:225], v162 offset:7168
	global_load_lds_dwordx4 v[142:143], off
	v_lshl_add_u64 v[142:143], s[0:1], 0, v[138:139]
	s_add_i32 m0, s93, 0xe000
	s_nop 0
	global_load_lds_dwordx4 v[142:143], off
	s_waitcnt lgkmcnt(8)
	s_barrier
	s_waitcnt lgkmcnt(0)
	s_setprio 1
	s_waitcnt lgkmcnt(0)
	v_mfma_f32_16x16x32_bf16 v[126:129], v[164:167], v[194:197], v[126:129]
	v_mfma_f32_16x16x32_bf16 v[126:129], v[182:185], v[198:201], v[126:129]
	v_mfma_f32_16x16x32_bf16 v[122:125], v[186:189], v[194:197], v[122:125]
	v_mfma_f32_16x16x32_bf16 v[122:125], v[190:193], v[198:201], v[122:125]
	v_mfma_f32_16x16x32_bf16 v[118:121], v[164:167], v[202:205], v[118:121]
	v_mfma_f32_16x16x32_bf16 v[118:121], v[182:185], v[206:209], v[118:121]
	v_mfma_f32_16x16x32_bf16 v[110:113], v[186:189], v[202:205], v[110:113]
	v_mfma_f32_16x16x32_bf16 v[110:113], v[190:193], v[206:209], v[110:113]
	v_mfma_f32_16x16x32_bf16 v[102:105], v[164:167], v[210:213], v[102:105]
	v_mfma_f32_16x16x32_bf16 v[102:105], v[182:185], v[214:217], v[102:105]
	v_mfma_f32_16x16x32_bf16 v[94:97], v[186:189], v[210:213], v[94:97]
	v_mfma_f32_16x16x32_bf16 v[94:97], v[190:193], v[214:217], v[94:97]
	v_mfma_f32_16x16x32_bf16 v[86:89], v[164:167], v[218:221], v[86:89]
	v_mfma_f32_16x16x32_bf16 v[86:89], v[182:185], v[222:225], v[86:89]
	v_mfma_f32_16x16x32_bf16 v[78:81], v[186:189], v[218:221], v[78:81]
	s_barrier
; #define PG8_STAGE(bufoff, gbase, voff) do { _Pragma("unroll") for (int _i = 0; _i < 2; ++_i) \
;         __builtin_amdgcn_global_load_lds((const unsigned*)((const char*)(gbase) + (voff)[_i]), (LAS unsigned*)(lds + (bufoff) + ldsw + _i * 8192), 16, 0, 0); } while (0)
; #define PG8_LDA(dst, b, h) do { _Pragma("unroll") for (int m = 0; m < 4; ++m) _Pragma("unroll") for (int k = 0; k < 2; ++k) dst[m][k] = *(const LAS bf16x8*)(lds + PG8_SA(b, h) + aoff + m * 2048 + k * 1024); } while (0)
; #define PG8_LDB(dst, b, h) do { _Pragma("unroll") for (int n = 0; n < 2; ++n) _Pragma("unroll") for (int k = 0; k < 2; ++k) dst[n][k] = *(const LAS bf16x8*)(lds + PG8_SB(b, h) + boff + n * 2048 + k * 1024); } while (0)
; #define PG8_MMA(ai, bj, At, Bt) do { __builtin_amdgcn_s_setprio(1); _Pragma("unroll") for (int m = 0; m < 4; ++m) _Pragma("unroll") for (int n = 0; n < 2; ++n) _Pragma("unroll") for (int k = 0; k < 2; ++k) \
;         acc[ai][bj][m][n] = __builtin_amdgcn_mfma_f32_16x16x32_bf16(Bt[n][k], At[m][k], acc[ai][bj][m][n], 0, 0, 0); __builtin_amdgcn_s_setprio(0); } while (0)
; #define PG8_WAIT_V(n) asm volatile("s_waitcnt vmcnt(" #n ")" ::: "memory")
; #define PG8_WAIT_L(n) asm volatile("s_waitcnt lgkmcnt(" #n ")" ::: "memory")
; #define PG8_BAR __builtin_amdgcn_s_barrier()
; #define PG8_SCHED __builtin_amdgcn_sched_barrier(0)
; template <class Epi, class Sched>
; __device__ __forceinline__ void gemm_phase(LAS unsigned char* lds, const Gemm g, const Sched& S, const Epi& E) {
;     ...
;             PG8_WAIT_L(8); PG8_BAR; PG8_WAIT_L(0); PG8_MMA(0, 0, At, B0); PG8_BAR; PG8_SCHED;
;             PG8_LDB(B1, 0, 1); PG8_STAGE(PG8_SB(0, 0), b2, voffB);
;             PG8_BAR; PG8_WAIT_L(0); PG8_MMA(0, 1, At, B1); PG8_BAR;
;             PG8_LDA(At, 0, 1); PG8_STAGE(PG8_SA(0, 0), a2, voffA);
;             PG8_BAR; PG8_WAIT_L(0); PG8_MMA(1, 0, At, B0); PG8_BAR; PG8_SCHED;
;             PG8_STAGE(PG8_SB(0, 1), b2 + hstep, voffB);
;             PG8_WAIT_V(6); PG8_BAR; PG8_MMA(1, 1, At, B1); PG8_BAR;
;             PG8_LDB(B0, 1, 0); PG8_SCHED; PG8_LDA(At, 1, 0); PG8_STAGE(PG8_SA(0, 1), a2 + hstep, voffA);
;             PG8_WAIT_L(8); PG8_BAR; PG8_WAIT_L(0); PG8_MMA(0, 0, At, B0); PG8_BAR; PG8_SCHED;
	v_mfma_f32_16x16x32_bf16 v[78:81], v[190:193], v[222:225], v[78:81]
	s_setprio 0
	s_add_i32 s51, 0, 0x14000
	v_add_u32_e32 v142, s51, v144
	s_add_i32 s24, s39, s86
	ds_read_b128 v[226:229], v142
	ds_read_b128 v[230:233], v142 offset:1024
	ds_read_b128 v[234:237], v142 offset:2048
	ds_read_b128 v[238:241], v142 offset:3072
	v_lshl_add_u64 v[142:143], s[36:37], 0, v[134:135]
	s_mov_b32 m0, s24
	v_lshl_add_u64 v[168:169], s[36:37], 0, v[130:131]
	global_load_lds_dwordx4 v[142:143], off
	s_add_i32 m0, s24, 0x2000
	s_nop 0
	global_load_lds_dwordx4 v[168:169], off
	s_barrier
	s_waitcnt lgkmcnt(0)
	s_setprio 1
	s_waitcnt lgkmcnt(0)
	v_mfma_f32_16x16x32_bf16 v[114:117], v[226:229], v[194:197], v[114:117]
	v_mfma_f32_16x16x32_bf16 v[114:117], v[230:233], v[198:201], v[114:117]
	v_mfma_f32_16x16x32_bf16 v[106:109], v[234:237], v[194:197], v[106:109]
	v_mfma_f32_16x16x32_bf16 v[106:109], v[238:241], v[198:201], v[106:109]
	v_mfma_f32_16x16x32_bf16 v[98:101], v[226:229], v[202:205], v[98:101]
	v_mfma_f32_16x16x32_bf16 v[98:101], v[230:233], v[206:209], v[98:101]
	v_mfma_f32_16x16x32_bf16 v[90:93], v[234:237], v[202:205], v[90:93]
	v_mfma_f32_16x16x32_bf16 v[90:93], v[238:241], v[206:209], v[90:93]
	v_mfma_f32_16x16x32_bf16 v[82:85], v[226:229], v[210:213], v[82:85]
	v_mfma_f32_16x16x32_bf16 v[82:85], v[230:233], v[214:217], v[82:85]
	v_mfma_f32_16x16x32_bf16 v[74:77], v[234:237], v[210:213], v[74:77]
	v_mfma_f32_16x16x32_bf16 v[74:77], v[238:241], v[214:217], v[74:77]
	v_mfma_f32_16x16x32_bf16 v[70:73], v[226:229], v[218:221], v[70:73]
	v_mfma_f32_16x16x32_bf16 v[70:73], v[230:233], v[222:225], v[70:73]
	v_mfma_f32_16x16x32_bf16 v[66:69], v[234:237], v[218:221], v[66:69]
	s_barrier
	v_mfma_f32_16x16x32_bf16 v[66:69], v[238:241], v[222:225], v[66:69]
	s_setprio 0
	s_mov_b32 m0, s93
	v_lshl_add_u64 v[242:243], vcc, 0, v[136:137]
	ds_read_b128 v[194:197], v162 offset:16384
	ds_read_b128 v[198:201], v162 offset:17408
	ds_read_b128 v[202:205], v162 offset:18432
	ds_read_b128 v[206:209], v162 offset:19456
	ds_read_b128 v[210:213], v162 offset:20480
	ds_read_b128 v[214:217], v162 offset:21504
	ds_read_b128 v[218:221], v162 offset:22528
	ds_read_b128 v[222:225], v162 offset:23552
	global_load_lds_dwordx4 v[242:243], off
	v_lshl_add_u64 v[244:245], vcc, 0, v[132:133]
	s_mov_b32 m0, s94
	s_nop 0
	global_load_lds_dwordx4 v[244:245], off
	s_waitcnt vmcnt(8)
	s_barrier
	s_waitcnt lgkmcnt(0)
	s_setprio 1
	s_waitcnt lgkmcnt(0)
	v_mfma_f32_16x16x32_bf16 v[62:65], v[164:167], v[194:197], v[62:65]
	v_mfma_f32_16x16x32_bf16 v[62:65], v[182:185], v[198:201], v[62:65]
	v_mfma_f32_16x16x32_bf16 v[58:61], v[186:189], v[194:197], v[58:61]
	v_mfma_f32_16x16x32_bf16 v[58:61], v[190:193], v[198:201], v[58:61]
	v_mfma_f32_16x16x32_bf16 v[54:57], v[164:167], v[202:205], v[54:57]
	v_mfma_f32_16x16x32_bf16 v[54:57], v[182:185], v[206:209], v[54:57]
	v_mfma_f32_16x16x32_bf16 v[46:49], v[186:189], v[202:205], v[46:49]
	v_mfma_f32_16x16x32_bf16 v[46:49], v[190:193], v[206:209], v[46:49]
	v_mfma_f32_16x16x32_bf16 v[38:41], v[164:167], v[210:213], v[38:41]
	v_mfma_f32_16x16x32_bf16 v[38:41], v[182:185], v[214:217], v[38:41]
	v_mfma_f32_16x16x32_bf16 v[30:33], v[186:189], v[210:213], v[30:33]
	v_mfma_f32_16x16x32_bf16 v[30:33], v[190:193], v[214:217], v[30:33]
	v_mfma_f32_16x16x32_bf16 v[22:25], v[164:167], v[218:221], v[22:25]
	v_mfma_f32_16x16x32_bf16 v[22:25], v[182:185], v[222:225], v[22:25]
	v_mfma_f32_16x16x32_bf16 v[14:17], v[186:189], v[218:221], v[14:17]
	s_barrier
	v_mfma_f32_16x16x32_bf16 v[14:17], v[190:193], v[222:225], v[14:17]
	s_setprio 0
	s_add_u32 s24, s36, 0x40000
	s_addc_u32 s25, s37, 0
	s_add_i32 s39, s51, s86
	v_lshl_add_u64 v[164:165], s[24:25], 0, v[134:135]
	s_mov_b32 m0, s39
	s_nop 0
	global_load_lds_dwordx4 v[164:165], off
	v_lshl_add_u64 v[164:165], s[24:25], 0, v[130:131]
	s_add_i32 m0, s39, 0x2000
	s_nop 0
	global_load_lds_dwordx4 v[164:165], off
	s_waitcnt vmcnt(6)
	s_barrier
	s_setprio 1
	v_add_u32_e32 v249, 0x18000, v144
	v_mfma_f32_16x16x32_bf16 v[50:53], v[226:229], v[194:197], v[50:53]
	v_mfma_f32_16x16x32_bf16 v[50:53], v[230:233], v[198:201], v[50:53]
	ds_read_b128 v[164:167], v249
	v_mfma_f32_16x16x32_bf16 v[42:45], v[234:237], v[194:197], v[42:45]
	v_mfma_f32_16x16x32_bf16 v[42:45], v[238:241], v[198:201], v[42:45]
	v_mfma_f32_16x16x32_bf16 v[34:37], v[226:229], v[202:205], v[34:37]
	v_mfma_f32_16x16x32_bf16 v[34:37], v[230:233], v[206:209], v[34:37]
	ds_read_b128 v[182:185], v249 offset:1024
	v_mfma_f32_16x16x32_bf16 v[26:29], v[234:237], v[202:205], v[26:29]
	v_mfma_f32_16x16x32_bf16 v[26:29], v[238:241], v[206:209], v[26:29]
	v_mfma_f32_16x16x32_bf16 v[18:21], v[226:229], v[210:213], v[18:21]
	v_mfma_f32_16x16x32_bf16 v[18:21], v[230:233], v[214:217], v[18:21]
	ds_read_b128 v[186:189], v249 offset:2048
	v_mfma_f32_16x16x32_bf16 v[10:13], v[234:237], v[210:213], v[10:13]
	v_mfma_f32_16x16x32_bf16 v[10:13], v[238:241], v[214:217], v[10:13]
	v_mfma_f32_16x16x32_bf16 v[6:9], v[226:229], v[218:221], v[6:9]
	v_mfma_f32_16x16x32_bf16 v[6:9], v[230:233], v[222:225], v[6:9]
	ds_read_b128 v[190:193], v249 offset:3072
	v_mfma_f32_16x16x32_bf16 v[2:5], v[234:237], v[218:221], v[2:5]
	s_barrier
	v_mfma_f32_16x16x32_bf16 v[2:5], v[238:241], v[222:225], v[2:5]
	s_setprio 0
	s_add_i32 s39, 0, 0x18000
	v_add_u32_e32 v163, s39, v144
	s_add_u32 s24, vcc_lo, 0x40000
	s_addc_u32 s25, vcc_hi, 0
	s_mov_b32 m0, s95
	v_lshl_add_u64 v[226:227], s[24:25], 0, v[136:137]
	ds_read_b128 v[194:197], v162 offset:32768
	ds_read_b128 v[198:201], v162 offset:33792
	ds_read_b128 v[202:205], v162 offset:34816
	ds_read_b128 v[206:209], v162 offset:35840
	ds_read_b128 v[210:213], v162 offset:36864
	ds_read_b128 v[214:217], v162 offset:37888
	ds_read_b128 v[218:221], v162 offset:38912
	ds_read_b128 v[222:225], v162 offset:39936
	global_load_lds_dwordx4 v[226:227], off
	v_lshl_add_u64 v[226:227], s[24:25], 0, v[132:133]
	s_mov_b32 m0, s96
	s_nop 0
	global_load_lds_dwordx4 v[226:227], off
	s_waitcnt lgkmcnt(8)
	s_barrier
; #define PG8_STAGE(bufoff, gbase, voff) do { _Pragma("unroll") for (int _i = 0; _i < 2; ++_i) \
;         __builtin_amdgcn_global_load_lds((const unsigned*)((const char*)(gbase) + (voff)[_i]), (LAS unsigned*)(lds + (bufoff) + ldsw + _i * 8192), 16, 0, 0); } while (0)
; #define PG8_LDA(dst, b, h) do { _Pragma("unroll") for (int m = 0; m < 4; ++m) _Pragma("unroll") for (int k = 0; k < 2; ++k) dst[m][k] = *(const LAS bf16x8*)(lds + PG8_SA(b, h) + aoff + m * 2048 + k * 1024); } while (0)
; #define PG8_LDB(dst, b, h) do { _Pragma("unroll") for (int n = 0; n < 2; ++n) _Pragma("unroll") for (int k = 0; k < 2; ++k) dst[n][k] = *(const LAS bf16x8*)(lds + PG8_SB(b, h) + boff + n * 2048 + k * 1024); } while (0)
; #define PG8_MMA(ai, bj, At, Bt) do { __builtin_amdgcn_s_setprio(1); _Pragma("unroll") for (int m = 0; m < 4; ++m) _Pragma("unroll") for (int n = 0; n < 2; ++n) _Pragma("unroll") for (int k = 0; k < 2; ++k) \
;         acc[ai][bj][m][n] = __builtin_amdgcn_mfma_f32_16x16x32_bf16(Bt[n][k], At[m][k], acc[ai][bj][m][n], 0, 0, 0); __builtin_amdgcn_s_setprio(0); } while (0)
; #define PG8_WAIT_V(n) asm volatile("s_waitcnt vmcnt(" #n ")" ::: "memory")
; #define PG8_WAIT_L(n) asm volatile("s_waitcnt lgkmcnt(" #n ")" ::: "memory")
; #define PG8_BAR __builtin_amdgcn_s_barrier()
; #define PG8_SCHED __builtin_amdgcn_sched_barrier(0)
; template <class Epi, class Sched>
; __device__ __forceinline__ void gemm_phase(LAS unsigned char* lds, const Gemm g, const Sched& S, const Epi& E) {
;     ...
;             PG8_WAIT_L(8); PG8_BAR; PG8_WAIT_L(0); PG8_MMA(0, 0, At, B0); PG8_BAR; PG8_SCHED;
;             PG8_LDB(B1, 1, 1); PG8_STAGE(PG8_SB(1, 0), b3, voffB);
;             PG8_BAR; PG8_WAIT_L(0); PG8_MMA(0, 1, At, B1); PG8_BAR;
;             PG8_LDA(At, 1, 1); PG8_STAGE(PG8_SA(1, 0), a3, voffA);
;             PG8_BAR; PG8_WAIT_L(0); PG8_MMA(1, 0, At, B0); PG8_BAR; PG8_SCHED;
;             PG8_STAGE(PG8_SB(1, 1), b3 + hstep, voffB);
;             PG8_WAIT_V(6); PG8_BAR; PG8_MMA(1, 1, At, B1); PG8_BAR;
;         }
;         if (wr == 0) PG8_BAR;
	s_waitcnt lgkmcnt(0)
	s_setprio 1
	s_waitcnt lgkmcnt(0)
	v_mfma_f32_16x16x32_bf16 v[126:129], v[164:167], v[194:197], v[126:129]
	v_mfma_f32_16x16x32_bf16 v[126:129], v[182:185], v[198:201], v[126:129]
	v_mfma_f32_16x16x32_bf16 v[122:125], v[186:189], v[194:197], v[122:125]
	v_mfma_f32_16x16x32_bf16 v[122:125], v[190:193], v[198:201], v[122:125]
	v_mfma_f32_16x16x32_bf16 v[118:121], v[164:167], v[202:205], v[118:121]
	v_mfma_f32_16x16x32_bf16 v[118:121], v[182:185], v[206:209], v[118:121]
	v_mfma_f32_16x16x32_bf16 v[110:113], v[186:189], v[202:205], v[110:113]
	v_mfma_f32_16x16x32_bf16 v[110:113], v[190:193], v[206:209], v[110:113]
	v_mfma_f32_16x16x32_bf16 v[102:105], v[164:167], v[210:213], v[102:105]
	v_mfma_f32_16x16x32_bf16 v[102:105], v[182:185], v[214:217], v[102:105]
	v_mfma_f32_16x16x32_bf16 v[94:97], v[186:189], v[210:213], v[94:97]
	v_mfma_f32_16x16x32_bf16 v[94:97], v[190:193], v[214:217], v[94:97]
	v_mfma_f32_16x16x32_bf16 v[86:89], v[164:167], v[218:221], v[86:89]
	v_mfma_f32_16x16x32_bf16 v[86:89], v[182:185], v[222:225], v[86:89]
	v_mfma_f32_16x16x32_bf16 v[78:81], v[186:189], v[218:221], v[78:81]
	s_barrier
	v_mfma_f32_16x16x32_bf16 v[78:81], v[190:193], v[222:225], v[78:81]
	s_setprio 0
	s_add_i32 s51, 0, 0x1c000
	s_add_i32 s24, s39, s86
	v_add_u32_e32 v163, s51, v144
	v_lshl_add_u64 v[142:143], v[142:143], 0, s[12:13]
	s_mov_b32 m0, s24
	ds_read_b128 v[226:229], v163
	ds_read_b128 v[230:233], v163 offset:1024
	ds_read_b128 v[234:237], v163 offset:2048
	ds_read_b128 v[238:241], v163 offset:3072
	global_load_lds_dwordx4 v[142:143], off
	v_lshl_add_u64 v[142:143], v[168:169], 0, s[12:13]
	s_add_i32 m0, s24, 0x2000
	s_nop 0
	global_load_lds_dwordx4 v[142:143], off
	s_barrier
	s_waitcnt lgkmcnt(0)
	s_setprio 1
	s_waitcnt lgkmcnt(0)
	v_mfma_f32_16x16x32_bf16 v[114:117], v[226:229], v[194:197], v[114:117]
	v_mfma_f32_16x16x32_bf16 v[114:117], v[230:233], v[198:201], v[114:117]
	v_mfma_f32_16x16x32_bf16 v[106:109], v[234:237], v[194:197], v[106:109]
	v_mfma_f32_16x16x32_bf16 v[106:109], v[238:241], v[198:201], v[106:109]
	v_mfma_f32_16x16x32_bf16 v[98:101], v[226:229], v[202:205], v[98:101]
	v_mfma_f32_16x16x32_bf16 v[98:101], v[230:233], v[206:209], v[98:101]
	v_mfma_f32_16x16x32_bf16 v[90:93], v[234:237], v[202:205], v[90:93]
	v_mfma_f32_16x16x32_bf16 v[90:93], v[238:241], v[206:209], v[90:93]
	v_mfma_f32_16x16x32_bf16 v[82:85], v[226:229], v[210:213], v[82:85]
	v_mfma_f32_16x16x32_bf16 v[82:85], v[230:233], v[214:217], v[82:85]
	v_mfma_f32_16x16x32_bf16 v[74:77], v[234:237], v[210:213], v[74:77]
	v_mfma_f32_16x16x32_bf16 v[74:77], v[238:241], v[214:217], v[74:77]
	v_mfma_f32_16x16x32_bf16 v[70:73], v[226:229], v[218:221], v[70:73]
	v_mfma_f32_16x16x32_bf16 v[70:73], v[230:233], v[222:225], v[70:73]
	v_mfma_f32_16x16x32_bf16 v[66:69], v[234:237], v[218:221], v[66:69]
	s_barrier
	v_mfma_f32_16x16x32_bf16 v[66:69], v[238:241], v[222:225], v[66:69]
	s_setprio 0
	s_mov_b32 m0, s97
	v_lshl_add_u64 v[142:143], v[242:243], 0, s[12:13]
	ds_read_b128 v[194:197], v162 offset:49152
	ds_read_b128 v[198:201], v162 offset:50176
	ds_read_b128 v[202:205], v162 offset:51200
	ds_read_b128 v[206:209], v162 offset:52224
	ds_read_b128 v[210:213], v162 offset:53248
	ds_read_b128 v[214:217], v162 offset:54272
	ds_read_b128 v[218:221], v162 offset:55296
	ds_read_b128 v[222:225], v162 offset:56320
	global_load_lds_dwordx4 v[142:143], off
	v_lshl_add_u64 v[142:143], v[244:245], 0, s[12:13]
	s_mov_b32 m0, s98
	s_nop 0
	global_load_lds_dwordx4 v[142:143], off
	s_waitcnt vmcnt(8)
	s_barrier
	s_waitcnt lgkmcnt(0)
	s_setprio 1
	s_waitcnt lgkmcnt(0)
	v_mfma_f32_16x16x32_bf16 v[62:65], v[164:167], v[194:197], v[62:65]
	v_mfma_f32_16x16x32_bf16 v[62:65], v[182:185], v[198:201], v[62:65]
	v_mfma_f32_16x16x32_bf16 v[58:61], v[186:189], v[194:197], v[58:61]
	v_mfma_f32_16x16x32_bf16 v[58:61], v[190:193], v[198:201], v[58:61]
	v_mfma_f32_16x16x32_bf16 v[54:57], v[164:167], v[202:205], v[54:57]
	v_mfma_f32_16x16x32_bf16 v[54:57], v[182:185], v[206:209], v[54:57]
	v_mfma_f32_16x16x32_bf16 v[46:49], v[186:189], v[202:205], v[46:49]
	v_mfma_f32_16x16x32_bf16 v[46:49], v[190:193], v[206:209], v[46:49]
	v_mfma_f32_16x16x32_bf16 v[38:41], v[164:167], v[210:213], v[38:41]
	v_mfma_f32_16x16x32_bf16 v[38:41], v[182:185], v[214:217], v[38:41]
	v_mfma_f32_16x16x32_bf16 v[30:33], v[186:189], v[210:213], v[30:33]
	v_mfma_f32_16x16x32_bf16 v[30:33], v[190:193], v[214:217], v[30:33]
	v_mfma_f32_16x16x32_bf16 v[22:25], v[164:167], v[218:221], v[22:25]
	v_mfma_f32_16x16x32_bf16 v[22:25], v[182:185], v[222:225], v[22:25]
	v_mfma_f32_16x16x32_bf16 v[14:17], v[186:189], v[218:221], v[14:17]
	s_barrier
	v_mfma_f32_16x16x32_bf16 v[14:17], v[190:193], v[222:225], v[14:17]
	s_setprio 0
	s_add_u32 s24, s36, 0x40080
	s_addc_u32 s25, s37, 0
	s_add_i32 s36, s51, s86
	v_lshl_add_u64 v[142:143], s[24:25], 0, v[134:135]
	s_mov_b32 m0, s36
	s_nop 0
	global_load_lds_dwordx4 v[142:143], off
	v_lshl_add_u64 v[142:143], s[24:25], 0, v[130:131]
	s_add_i32 m0, s36, 0x2000
	s_nop 0
	global_load_lds_dwordx4 v[142:143], off
	s_waitcnt vmcnt(6)
	s_barrier
	s_setprio 1
	v_add_u32_e32 v249, 0x10000, v144
	v_mfma_f32_16x16x32_bf16 v[50:53], v[226:229], v[194:197], v[50:53]
	v_mfma_f32_16x16x32_bf16 v[50:53], v[230:233], v[198:201], v[50:53]
	ds_read_b128 v[164:167], v249
	v_mfma_f32_16x16x32_bf16 v[42:45], v[234:237], v[194:197], v[42:45]
	v_mfma_f32_16x16x32_bf16 v[42:45], v[238:241], v[198:201], v[42:45]
	v_mfma_f32_16x16x32_bf16 v[34:37], v[226:229], v[202:205], v[34:37]
	v_mfma_f32_16x16x32_bf16 v[34:37], v[230:233], v[206:209], v[34:37]
	ds_read_b128 v[182:185], v249 offset:1024
	v_mfma_f32_16x16x32_bf16 v[26:29], v[234:237], v[202:205], v[26:29]
	v_mfma_f32_16x16x32_bf16 v[26:29], v[238:241], v[206:209], v[26:29]
	v_mfma_f32_16x16x32_bf16 v[18:21], v[226:229], v[210:213], v[18:21]
	v_mfma_f32_16x16x32_bf16 v[18:21], v[230:233], v[214:217], v[18:21]
	ds_read_b128 v[186:189], v249 offset:2048
	v_mfma_f32_16x16x32_bf16 v[10:13], v[234:237], v[210:213], v[10:13]
	v_mfma_f32_16x16x32_bf16 v[10:13], v[238:241], v[214:217], v[10:13]
	v_mfma_f32_16x16x32_bf16 v[6:9], v[226:229], v[218:221], v[6:9]
	v_mfma_f32_16x16x32_bf16 v[6:9], v[230:233], v[222:225], v[6:9]
	ds_read_b128 v[190:193], v249 offset:3072
	v_mfma_f32_16x16x32_bf16 v[2:5], v[234:237], v[218:221], v[2:5]
	s_barrier
	v_mfma_f32_16x16x32_bf16 v[2:5], v[238:241], v[222:225], v[2:5]
	s_setprio 0
	s_add_i32 s38, s38, 2
	s_add_u32 s35, s35, 0x100
	s_addc_u32 s50, s50, 0
	s_add_u32 s0, s0, 0x100
	s_addc_u32 s1, s1, 0
	s_cmp_gt_u32 s38, 13
	s_cbranch_scc0 .LBB0_416
	s_waitcnt lgkmcnt(0)
	s_and_b64 vcc, exec, s[44:45]
	s_cbranch_vccz .LBB0_419
	s_barrier

; #define PG8_STAGE(bufoff, gbase, voff) do { _Pragma("unroll") for (int _i = 0; _i < 2; ++_i) \
;         __builtin_amdgcn_global_load_lds((const unsigned*)((const char*)(gbase) + (voff)[_i]), (LAS unsigned*)(lds + (bufoff) + ldsw + _i * 8192), 16, 0, 0); } while (0)
; #define PG8_LDA(dst, b, h) do { _Pragma("unroll") for (int m = 0; m < 4; ++m) _Pragma("unroll") for (int k = 0; k < 2; ++k) dst[m][k] = *(const LAS bf16x8*)(lds + PG8_SA(b, h) + aoff + m * 2048 + k * 1024); } while (0)
; #define PG8_LDB(dst, b, h) do { _Pragma("unroll") for (int n = 0; n < 2; ++n) _Pragma("unroll") for (int k = 0; k < 2; ++k) dst[n][k] = *(const LAS bf16x8*)(lds + PG8_SB(b, h) + boff + n * 2048 + k * 1024); } while (0)
; #define PG8_MMA(ai, bj, At, Bt) do { __builtin_amdgcn_s_setprio(1); _Pragma("unroll") for (int m = 0; m < 4; ++m) _Pragma("unroll") for (int n = 0; n < 2; ++n) _Pragma("unroll") for (int k = 0; k < 2; ++k) \
;         acc[ai][bj][m][n] = __builtin_amdgcn_mfma_f32_16x16x32_bf16(Bt[n][k], At[m][k], acc[ai][bj][m][n], 0, 0, 0); __builtin_amdgcn_s_setprio(0); } while (0)
; #define PG8_WAIT_L(n) asm volatile("s_waitcnt lgkmcnt(" #n ")" ::: "memory")
; template <class Epi, class Sched>
; __device__ __forceinline__ void gemm_phase(LAS unsigned char* lds, const Gemm g, const Sched& S, const Epi& E) {
;     ...
;         const bool has_next = S.next(ui + 1, nxt);
;         const char* nA = has_next ? PG8_APANEL(nxt.pm) : cA; const char* nB = has_next ? (const char*)g.Bt + (size_t)nxt.pn * tstep : cB;
;         for (int t = 0; t < nt; t += 2) {
;             const bool last = (t == nt - 2);
;             const char* a1 = cA + (size_t)(t + 1) * kstep;
;             const char* a2 = last ? nA : cA + (size_t)(t + 2) * kstep; const char* b2 = last ? nB : cB + (size_t)(t + 2) * kstep;
;             const char* a3 = a2 + kstep; const char* b3 = b2 + kstep;
;             PG8_LDB(B0, 0, 0); PG8_SCHED; PG8_LDA(At, 0, 0); PG8_STAGE(PG8_SA(1, 1), a1 + hstep, voffA);
;             PG8_WAIT_L(8); PG8_BAR; PG8_WAIT_L(0); PG8_MMA(0, 0, At, B0); PG8_BAR; PG8_SCHED;
;     ...
; #pragma unroll
;         for (int a = 0; a < 2; ++a)
; #pragma unroll
;             for (int b = 0; b < 2; ++b)
; #pragma unroll
;                 for (int m = 0; m < 4; ++m)
; #pragma unroll
;                     for (int n = 0; n < 2; ++n) acc[a][b][m][n] = (f32x4){0.f, 0.f, 0.f, 0.f};
.LBB0_556:
	s_ashr_i32 s45, s44, 31
	s_lshl_b64 s[24:25], s[44:45], 19
	s_add_u32 s60, s86, s24
	s_addc_u32 s61, s93, s25
	s_and_b64 s[0:1], s[0:1], exec
	s_cselect_b32 s45, s61, s49
	s_cselect_b32 s47, s60, s48
	s_add_u32 s35, s48, 0x100
	s_addc_u32 s50, s49, 0
	s_add_u32 s0, s38, 0x40080
	v_mov_b32_e32 v2, 0
	s_addc_u32 s1, s39, 0
	s_mov_b32 s38, -2
	v_mov_b32_e32 v3, v2
	v_mov_b32_e32 v4, v2
	v_mov_b32_e32 v5, v2
	v_mov_b32_e32 v6, v2
	v_mov_b32_e32 v7, v2
	v_mov_b32_e32 v8, v2
	v_mov_b32_e32 v9, v2
	v_mov_b32_e32 v18, v2
	v_mov_b32_e32 v19, v2
	v_mov_b32_e32 v20, v2
	v_mov_b32_e32 v21, v2
	v_mov_b32_e32 v22, v2
	v_mov_b32_e32 v23, v2
	v_mov_b32_e32 v24, v2
	v_mov_b32_e32 v25, v2
	v_mov_b32_e32 v34, v2
	v_mov_b32_e32 v35, v2
	v_mov_b32_e32 v36, v2
	v_mov_b32_e32 v37, v2
	v_mov_b32_e32 v38, v2
	v_mov_b32_e32 v39, v2
	v_mov_b32_e32 v40, v2
	v_mov_b32_e32 v41, v2
	v_mov_b32_e32 v50, v2
	v_mov_b32_e32 v51, v2
	v_mov_b32_e32 v52, v2
	v_mov_b32_e32 v53, v2
	v_mov_b32_e32 v54, v2
	v_mov_b32_e32 v55, v2
	v_mov_b32_e32 v56, v2
	v_mov_b32_e32 v57, v2
	v_mov_b32_e32 v10, v2
	v_mov_b32_e32 v11, v2
	v_mov_b32_e32 v12, v2
	v_mov_b32_e32 v13, v2
	v_mov_b32_e32 v14, v2
	v_mov_b32_e32 v15, v2
	v_mov_b32_e32 v16, v2
	v_mov_b32_e32 v17, v2
	v_mov_b32_e32 v26, v2
	v_mov_b32_e32 v27, v2
	v_mov_b32_e32 v28, v2
	v_mov_b32_e32 v29, v2
	v_mov_b32_e32 v30, v2
	v_mov_b32_e32 v31, v2
	v_mov_b32_e32 v32, v2
	v_mov_b32_e32 v33, v2
	v_mov_b32_e32 v42, v2
	v_mov_b32_e32 v43, v2
	v_mov_b32_e32 v44, v2
	v_mov_b32_e32 v45, v2
	v_mov_b32_e32 v46, v2
	v_mov_b32_e32 v47, v2
	v_mov_b32_e32 v48, v2
	v_mov_b32_e32 v49, v2
	v_mov_b32_e32 v58, v2
	v_mov_b32_e32 v59, v2
	v_mov_b32_e32 v60, v2
	v_mov_b32_e32 v61, v2
	v_mov_b32_e32 v62, v2
	v_mov_b32_e32 v63, v2
	v_mov_b32_e32 v64, v2
	v_mov_b32_e32 v65, v2
	v_mov_b32_e32 v66, v2
	v_mov_b32_e32 v67, v2
	v_mov_b32_e32 v68, v2
	v_mov_b32_e32 v69, v2
	v_mov_b32_e32 v70, v2
	v_mov_b32_e32 v71, v2
	v_mov_b32_e32 v72, v2
	v_mov_b32_e32 v73, v2
	v_mov_b32_e32 v82, v2
	v_mov_b32_e32 v83, v2
	v_mov_b32_e32 v84, v2
	v_mov_b32_e32 v85, v2
	v_mov_b32_e32 v86, v2
	v_mov_b32_e32 v87, v2
	v_mov_b32_e32 v88, v2
	v_mov_b32_e32 v89, v2
	v_mov_b32_e32 v98, v2
	v_mov_b32_e32 v99, v2
	v_mov_b32_e32 v100, v2
	v_mov_b32_e32 v101, v2
	v_mov_b32_e32 v102, v2
	v_mov_b32_e32 v103, v2
	v_mov_b32_e32 v104, v2
	v_mov_b32_e32 v105, v2
	v_mov_b32_e32 v114, v2
	v_mov_b32_e32 v115, v2
	v_mov_b32_e32 v116, v2
	v_mov_b32_e32 v117, v2
	v_mov_b32_e32 v118, v2
	v_mov_b32_e32 v119, v2
	v_mov_b32_e32 v120, v2
	v_mov_b32_e32 v121, v2
	v_mov_b32_e32 v74, v2
	v_mov_b32_e32 v75, v2
	v_mov_b32_e32 v76, v2
	v_mov_b32_e32 v77, v2
	v_mov_b32_e32 v78, v2
	v_mov_b32_e32 v79, v2
	v_mov_b32_e32 v80, v2
	v_mov_b32_e32 v81, v2
	v_mov_b32_e32 v90, v2
	v_mov_b32_e32 v91, v2
	v_mov_b32_e32 v92, v2
	v_mov_b32_e32 v93, v2
	v_mov_b32_e32 v94, v2
	v_mov_b32_e32 v95, v2
	v_mov_b32_e32 v96, v2
	v_mov_b32_e32 v97, v2
	v_mov_b32_e32 v106, v2
	v_mov_b32_e32 v107, v2
	v_mov_b32_e32 v108, v2
	v_mov_b32_e32 v109, v2
	v_mov_b32_e32 v110, v2
	v_mov_b32_e32 v111, v2
	v_mov_b32_e32 v112, v2
	v_mov_b32_e32 v113, v2
	v_mov_b32_e32 v122, v2
	v_mov_b32_e32 v123, v2
	v_mov_b32_e32 v124, v2
	v_mov_b32_e32 v125, v2
	v_mov_b32_e32 v126, v2
	v_mov_b32_e32 v127, v2
	v_mov_b32_e32 v128, v2
	v_mov_b32_e32 v129, v2
	v_add_u32_e32 v249, 0x10000, v164
	ds_read_b128 v[142:145], v249
	ds_read_b128 v[182:185], v249 offset:1024
	ds_read_b128 v[186:189], v249 offset:2048
	ds_read_b128 v[190:193], v249 offset:3072
.LBB0_557:
	s_add_u32 s24, s0, 0xfffc0080
	s_addc_u32 s25, s1, -1
	s_add_i32 s39, 0, 0x10000
	v_add_u32_e32 v162, s39, v164
	s_cmp_eq_u32 s38, 12
	s_cselect_b32 vcc_hi, s77, s25
	s_cselect_b32 vcc_lo, s76, s24
	s_cselect_b32 s49, s45, s50
	s_cselect_b32 s48, s47, s35
	v_lshl_add_u64 v[162:163], s[0:1], 0, v[140:141]
	s_add_i32 m0, s95, 0xc000
	ds_read_b128 v[194:197], v166
	ds_read_b128 v[198:201], v166 offset:1024
	ds_read_b128 v[202:205], v166 offset:2048
	ds_read_b128 v[206:209], v166 offset:3072
	ds_read_b128 v[210:213], v166 offset:4096
	ds_read_b128 v[214:217], v166 offset:5120
	ds_read_b128 v[218:221], v166 offset:6144
	ds_read_b128 v[222:225], v166 offset:7168
	global_load_lds_dwordx4 v[162:163], off
	v_lshl_add_u64 v[162:163], s[0:1], 0, v[138:139]
	s_add_i32 m0, s95, 0xe000
	s_nop 0
	global_load_lds_dwordx4 v[162:163], off
	s_waitcnt lgkmcnt(8)
	s_barrier
	s_waitcnt lgkmcnt(0)
	s_setprio 1
	s_waitcnt lgkmcnt(0)
	v_mfma_f32_16x16x32_bf16 v[126:129], v[142:145], v[194:197], v[126:129]
	v_mfma_f32_16x16x32_bf16 v[126:129], v[182:185], v[198:201], v[126:129]
	v_mfma_f32_16x16x32_bf16 v[122:125], v[186:189], v[194:197], v[122:125]
	v_mfma_f32_16x16x32_bf16 v[122:125], v[190:193], v[198:201], v[122:125]
	v_mfma_f32_16x16x32_bf16 v[110:113], v[142:145], v[202:205], v[110:113]
	v_mfma_f32_16x16x32_bf16 v[110:113], v[182:185], v[206:209], v[110:113]
	v_mfma_f32_16x16x32_bf16 v[106:109], v[186:189], v[202:205], v[106:109]
	v_mfma_f32_16x16x32_bf16 v[106:109], v[190:193], v[206:209], v[106:109]
	v_mfma_f32_16x16x32_bf16 v[94:97], v[142:145], v[210:213], v[94:97]
	v_mfma_f32_16x16x32_bf16 v[94:97], v[182:185], v[214:217], v[94:97]
	v_mfma_f32_16x16x32_bf16 v[90:93], v[186:189], v[210:213], v[90:93]
	v_mfma_f32_16x16x32_bf16 v[90:93], v[190:193], v[214:217], v[90:93]
	v_mfma_f32_16x16x32_bf16 v[78:81], v[142:145], v[218:221], v[78:81]
	v_mfma_f32_16x16x32_bf16 v[78:81], v[182:185], v[222:225], v[78:81]
	v_mfma_f32_16x16x32_bf16 v[74:77], v[186:189], v[218:221], v[74:77]
	s_barrier
; #define PG8_STAGE(bufoff, gbase, voff) do { _Pragma("unroll") for (int _i = 0; _i < 2; ++_i) \
;         __builtin_amdgcn_global_load_lds((const unsigned*)((const char*)(gbase) + (voff)[_i]), (LAS unsigned*)(lds + (bufoff) + ldsw + _i * 8192), 16, 0, 0); } while (0)
; #define PG8_LDA(dst, b, h) do { _Pragma("unroll") for (int m = 0; m < 4; ++m) _Pragma("unroll") for (int k = 0; k < 2; ++k) dst[m][k] = *(const LAS bf16x8*)(lds + PG8_SA(b, h) + aoff + m * 2048 + k * 1024); } while (0)
; #define PG8_LDB(dst, b, h) do { _Pragma("unroll") for (int n = 0; n < 2; ++n) _Pragma("unroll") for (int k = 0; k < 2; ++k) dst[n][k] = *(const LAS bf16x8*)(lds + PG8_SB(b, h) + boff + n * 2048 + k * 1024); } while (0)
; #define PG8_MMA(ai, bj, At, Bt) do { __builtin_amdgcn_s_setprio(1); _Pragma("unroll") for (int m = 0; m < 4; ++m) _Pragma("unroll") for (int n = 0; n < 2; ++n) _Pragma("unroll") for (int k = 0; k < 2; ++k) \
;         acc[ai][bj][m][n] = __builtin_amdgcn_mfma_f32_16x16x32_bf16(Bt[n][k], At[m][k], acc[ai][bj][m][n], 0, 0, 0); __builtin_amdgcn_s_setprio(0); } while (0)
; #define PG8_WAIT_V(n) asm volatile("s_waitcnt vmcnt(" #n ")" ::: "memory")
; #define PG8_WAIT_L(n) asm volatile("s_waitcnt lgkmcnt(" #n ")" ::: "memory")
; #define PG8_BAR __builtin_amdgcn_s_barrier()
; #define PG8_SCHED __builtin_amdgcn_sched_barrier(0)
; template <class Epi, class Sched>
; __device__ __forceinline__ void gemm_phase(LAS unsigned char* lds, const Gemm g, const Sched& S, const Epi& E) {
;     ...
;             PG8_WAIT_L(8); PG8_BAR; PG8_WAIT_L(0); PG8_MMA(0, 0, At, B0); PG8_BAR; PG8_SCHED;
;             PG8_LDB(B1, 0, 1); PG8_STAGE(PG8_SB(0, 0), b2, voffB);
;             PG8_BAR; PG8_WAIT_L(0); PG8_MMA(0, 1, At, B1); PG8_BAR;
;             PG8_LDA(At, 0, 1); PG8_STAGE(PG8_SA(0, 0), a2, voffA);
;             PG8_BAR; PG8_WAIT_L(0); PG8_MMA(1, 0, At, B0); PG8_BAR; PG8_SCHED;
;             PG8_STAGE(PG8_SB(0, 1), b2 + hstep, voffB);
;             PG8_WAIT_V(6); PG8_BAR; PG8_MMA(1, 1, At, B1); PG8_BAR;
;             PG8_LDB(B0, 1, 0); PG8_SCHED; PG8_LDA(At, 1, 0); PG8_STAGE(PG8_SA(0, 1), a2 + hstep, voffA);
;             PG8_WAIT_L(8); PG8_BAR; PG8_WAIT_L(0); PG8_MMA(0, 0, At, B0); PG8_BAR; PG8_SCHED;
	v_mfma_f32_16x16x32_bf16 v[74:77], v[190:193], v[222:225], v[74:77]
	s_setprio 0
	s_add_i32 s51, 0, 0x14000
	v_add_u32_e32 v162, s51, v164
	s_add_i32 s24, s39, s94
	ds_read_b128 v[226:229], v162
	ds_read_b128 v[230:233], v162 offset:1024
	ds_read_b128 v[234:237], v162 offset:2048
	ds_read_b128 v[238:241], v162 offset:3072
	v_lshl_add_u64 v[162:163], s[48:49], 0, v[134:135]
	s_mov_b32 m0, s24
	v_lshl_add_u64 v[168:169], s[48:49], 0, v[130:131]
	global_load_lds_dwordx4 v[162:163], off
	s_add_i32 m0, s24, 0x2000
	s_nop 0
	global_load_lds_dwordx4 v[168:169], off
	s_barrier
	s_waitcnt lgkmcnt(0)
	s_setprio 1
	s_waitcnt lgkmcnt(0)
	v_mfma_f32_16x16x32_bf16 v[118:121], v[226:229], v[194:197], v[118:121]
	v_mfma_f32_16x16x32_bf16 v[118:121], v[230:233], v[198:201], v[118:121]
	v_mfma_f32_16x16x32_bf16 v[114:117], v[234:237], v[194:197], v[114:117]
	v_mfma_f32_16x16x32_bf16 v[114:117], v[238:241], v[198:201], v[114:117]
	v_mfma_f32_16x16x32_bf16 v[102:105], v[226:229], v[202:205], v[102:105]
	v_mfma_f32_16x16x32_bf16 v[102:105], v[230:233], v[206:209], v[102:105]
	v_mfma_f32_16x16x32_bf16 v[98:101], v[234:237], v[202:205], v[98:101]
	v_mfma_f32_16x16x32_bf16 v[98:101], v[238:241], v[206:209], v[98:101]
	v_mfma_f32_16x16x32_bf16 v[86:89], v[226:229], v[210:213], v[86:89]
	v_mfma_f32_16x16x32_bf16 v[86:89], v[230:233], v[214:217], v[86:89]
	v_mfma_f32_16x16x32_bf16 v[82:85], v[234:237], v[210:213], v[82:85]
	v_mfma_f32_16x16x32_bf16 v[82:85], v[238:241], v[214:217], v[82:85]
	v_mfma_f32_16x16x32_bf16 v[70:73], v[226:229], v[218:221], v[70:73]
	v_mfma_f32_16x16x32_bf16 v[70:73], v[230:233], v[222:225], v[70:73]
	v_mfma_f32_16x16x32_bf16 v[66:69], v[234:237], v[218:221], v[66:69]
	s_barrier
	v_mfma_f32_16x16x32_bf16 v[66:69], v[238:241], v[222:225], v[66:69]
	s_setprio 0
	s_mov_b32 m0, s95
	v_lshl_add_u64 v[242:243], vcc, 0, v[136:137]
	ds_read_b128 v[194:197], v166 offset:16384
	ds_read_b128 v[198:201], v166 offset:17408
	ds_read_b128 v[202:205], v166 offset:18432
	ds_read_b128 v[206:209], v166 offset:19456
	ds_read_b128 v[210:213], v166 offset:20480
	ds_read_b128 v[214:217], v166 offset:21504
	ds_read_b128 v[218:221], v166 offset:22528
	ds_read_b128 v[222:225], v166 offset:23552
	global_load_lds_dwordx4 v[242:243], off
	v_lshl_add_u64 v[244:245], vcc, 0, v[132:133]
	s_mov_b32 m0, s96
	s_nop 0
	global_load_lds_dwordx4 v[244:245], off
	s_waitcnt vmcnt(8)
	s_barrier
	s_waitcnt lgkmcnt(0)
	s_setprio 1
	s_waitcnt lgkmcnt(0)
	v_mfma_f32_16x16x32_bf16 v[62:65], v[142:145], v[194:197], v[62:65]
	v_mfma_f32_16x16x32_bf16 v[62:65], v[182:185], v[198:201], v[62:65]
	v_mfma_f32_16x16x32_bf16 v[58:61], v[186:189], v[194:197], v[58:61]
	v_mfma_f32_16x16x32_bf16 v[58:61], v[190:193], v[198:201], v[58:61]
	v_mfma_f32_16x16x32_bf16 v[46:49], v[142:145], v[202:205], v[46:49]
	v_mfma_f32_16x16x32_bf16 v[46:49], v[182:185], v[206:209], v[46:49]
	v_mfma_f32_16x16x32_bf16 v[42:45], v[186:189], v[202:205], v[42:45]
	v_mfma_f32_16x16x32_bf16 v[42:45], v[190:193], v[206:209], v[42:45]
	v_mfma_f32_16x16x32_bf16 v[30:33], v[142:145], v[210:213], v[30:33]
	v_mfma_f32_16x16x32_bf16 v[30:33], v[182:185], v[214:217], v[30:33]
	v_mfma_f32_16x16x32_bf16 v[26:29], v[186:189], v[210:213], v[26:29]
	v_mfma_f32_16x16x32_bf16 v[26:29], v[190:193], v[214:217], v[26:29]
	v_mfma_f32_16x16x32_bf16 v[14:17], v[142:145], v[218:221], v[14:17]
	v_mfma_f32_16x16x32_bf16 v[14:17], v[182:185], v[222:225], v[14:17]
	v_mfma_f32_16x16x32_bf16 v[10:13], v[186:189], v[218:221], v[10:13]
	s_barrier
	v_mfma_f32_16x16x32_bf16 v[10:13], v[190:193], v[222:225], v[10:13]
	s_setprio 0
	s_add_u32 s24, s48, 0x40000
	s_addc_u32 s25, s49, 0
	s_add_i32 s39, s51, s94
	v_lshl_add_u64 v[142:143], s[24:25], 0, v[134:135]
	s_mov_b32 m0, s39
	s_nop 0
	global_load_lds_dwordx4 v[142:143], off
	v_lshl_add_u64 v[142:143], s[24:25], 0, v[130:131]
	s_add_i32 m0, s39, 0x2000
	s_nop 0
	global_load_lds_dwordx4 v[142:143], off
	s_waitcnt vmcnt(6)
	s_barrier
	s_setprio 1
	v_add_u32_e32 v249, 0x18000, v164
	v_mfma_f32_16x16x32_bf16 v[54:57], v[226:229], v[194:197], v[54:57]
	v_mfma_f32_16x16x32_bf16 v[54:57], v[230:233], v[198:201], v[54:57]
	ds_read_b128 v[142:145], v249
	v_mfma_f32_16x16x32_bf16 v[50:53], v[234:237], v[194:197], v[50:53]
	v_mfma_f32_16x16x32_bf16 v[50:53], v[238:241], v[198:201], v[50:53]
	v_mfma_f32_16x16x32_bf16 v[38:41], v[226:229], v[202:205], v[38:41]
	v_mfma_f32_16x16x32_bf16 v[38:41], v[230:233], v[206:209], v[38:41]
	ds_read_b128 v[182:185], v249 offset:1024
	v_mfma_f32_16x16x32_bf16 v[34:37], v[234:237], v[202:205], v[34:37]
	v_mfma_f32_16x16x32_bf16 v[34:37], v[238:241], v[206:209], v[34:37]
	v_mfma_f32_16x16x32_bf16 v[22:25], v[226:229], v[210:213], v[22:25]
	v_mfma_f32_16x16x32_bf16 v[22:25], v[230:233], v[214:217], v[22:25]
	ds_read_b128 v[186:189], v249 offset:2048
	v_mfma_f32_16x16x32_bf16 v[18:21], v[234:237], v[210:213], v[18:21]
	v_mfma_f32_16x16x32_bf16 v[18:21], v[238:241], v[214:217], v[18:21]
	v_mfma_f32_16x16x32_bf16 v[6:9], v[226:229], v[218:221], v[6:9]
	v_mfma_f32_16x16x32_bf16 v[6:9], v[230:233], v[222:225], v[6:9]
	ds_read_b128 v[190:193], v249 offset:3072
	v_mfma_f32_16x16x32_bf16 v[2:5], v[234:237], v[218:221], v[2:5]
	s_barrier
	v_mfma_f32_16x16x32_bf16 v[2:5], v[238:241], v[222:225], v[2:5]
	s_setprio 0
	s_add_i32 s39, 0, 0x18000
	v_add_u32_e32 v167, s39, v164
	s_add_u32 s24, vcc_lo, 0x40000
	s_addc_u32 s25, vcc_hi, 0
	s_mov_b32 m0, s97
	v_lshl_add_u64 v[226:227], s[24:25], 0, v[136:137]
	ds_read_b128 v[194:197], v166 offset:32768
	ds_read_b128 v[198:201], v166 offset:33792
	ds_read_b128 v[202:205], v166 offset:34816
	ds_read_b128 v[206:209], v166 offset:35840
	ds_read_b128 v[210:213], v166 offset:36864
	ds_read_b128 v[214:217], v166 offset:37888
	ds_read_b128 v[218:221], v166 offset:38912
	ds_read_b128 v[222:225], v166 offset:39936
	global_load_lds_dwordx4 v[226:227], off
	v_lshl_add_u64 v[226:227], s[24:25], 0, v[132:133]
	s_mov_b32 m0, s98
	s_nop 0
	global_load_lds_dwordx4 v[226:227], off
	s_waitcnt lgkmcnt(8)
	s_barrier
; #define PG8_STAGE(bufoff, gbase, voff) do { _Pragma("unroll") for (int _i = 0; _i < 2; ++_i) \
;         __builtin_amdgcn_global_load_lds((const unsigned*)((const char*)(gbase) + (voff)[_i]), (LAS unsigned*)(lds + (bufoff) + ldsw + _i * 8192), 16, 0, 0); } while (0)
; #define PG8_LDA(dst, b, h) do { _Pragma("unroll") for (int m = 0; m < 4; ++m) _Pragma("unroll") for (int k = 0; k < 2; ++k) dst[m][k] = *(const LAS bf16x8*)(lds + PG8_SA(b, h) + aoff + m * 2048 + k * 1024); } while (0)
; #define PG8_LDB(dst, b, h) do { _Pragma("unroll") for (int n = 0; n < 2; ++n) _Pragma("unroll") for (int k = 0; k < 2; ++k) dst[n][k] = *(const LAS bf16x8*)(lds + PG8_SB(b, h) + boff + n * 2048 + k * 1024); } while (0)
; #define PG8_WAIT_V(n) asm volatile("s_waitcnt vmcnt(" #n ")" ::: "memory")
; #define PG8_WAIT_L(n) asm volatile("s_waitcnt lgkmcnt(" #n ")" ::: "memory")
; #define PG8_BAR __builtin_amdgcn_s_barrier()
; template <class Epi, class Sched>
; __device__ __forceinline__ void gemm_phase(LAS unsigned char* lds, const Gemm g, const Sched& S, const Epi& E) {
;     ...
;             PG8_LDB(B0, 0, 0); PG8_SCHED; PG8_LDA(At, 0, 0); PG8_STAGE(PG8_SA(1, 1), a1 + hstep, voffA);
;             PG8_WAIT_L(8); PG8_BAR; PG8_WAIT_L(0); PG8_MMA(0, 0, At, B0); PG8_BAR; PG8_SCHED;
;             PG8_LDB(B1, 0, 1); PG8_STAGE(PG8_SB(0, 0), b2, voffB);
;             PG8_BAR; PG8_WAIT_L(0); PG8_MMA(0, 1, At, B1); PG8_BAR;
;             PG8_LDA(At, 0, 1); PG8_STAGE(PG8_SA(0, 0), a2, voffA);
;             PG8_BAR; PG8_WAIT_L(0); PG8_MMA(1, 0, At, B0); PG8_BAR; PG8_SCHED;
;             PG8_STAGE(PG8_SB(0, 1), b2 + hstep, voffB);
;             PG8_WAIT_V(6); PG8_BAR; PG8_MMA(1, 1, At, B1); PG8_BAR;
;             PG8_LDB(B0, 1, 0); PG8_SCHED; PG8_LDA(At, 1, 0); PG8_STAGE(PG8_SA(0, 1), a2 + hstep, voffA);
;             PG8_WAIT_L(8); PG8_BAR; PG8_WAIT_L(0); PG8_MMA(0, 0, At, B0); PG8_BAR; PG8_SCHED;
;             PG8_LDB(B1, 1, 1); PG8_STAGE(PG8_SB(1, 0), b3, voffB);
;             PG8_BAR; PG8_WAIT_L(0); PG8_MMA(0, 1, At, B1); PG8_BAR;
;             PG8_LDA(At, 1, 1); PG8_STAGE(PG8_SA(1, 0), a3, voffA);
;             PG8_BAR; PG8_WAIT_L(0); PG8_MMA(1, 0, At, B0); PG8_BAR; PG8_SCHED;
;             PG8_STAGE(PG8_SB(1, 1), b3 + hstep, voffB);
;             PG8_WAIT_V(6); PG8_BAR; PG8_MMA(1, 1, At, B1); PG8_BAR;
;         }
;         if (wr == 0) PG8_BAR;
	s_waitcnt lgkmcnt(0)
	s_setprio 1
	s_waitcnt lgkmcnt(0)
	v_mfma_f32_16x16x32_bf16 v[126:129], v[142:145], v[194:197], v[126:129]
	v_mfma_f32_16x16x32_bf16 v[126:129], v[182:185], v[198:201], v[126:129]
	v_mfma_f32_16x16x32_bf16 v[122:125], v[186:189], v[194:197], v[122:125]
	v_mfma_f32_16x16x32_bf16 v[122:125], v[190:193], v[198:201], v[122:125]
	v_mfma_f32_16x16x32_bf16 v[110:113], v[142:145], v[202:205], v[110:113]
	v_mfma_f32_16x16x32_bf16 v[110:113], v[182:185], v[206:209], v[110:113]
	v_mfma_f32_16x16x32_bf16 v[106:109], v[186:189], v[202:205], v[106:109]
	v_mfma_f32_16x16x32_bf16 v[106:109], v[190:193], v[206:209], v[106:109]
	v_mfma_f32_16x16x32_bf16 v[94:97], v[142:145], v[210:213], v[94:97]
	v_mfma_f32_16x16x32_bf16 v[94:97], v[182:185], v[214:217], v[94:97]
	v_mfma_f32_16x16x32_bf16 v[90:93], v[186:189], v[210:213], v[90:93]
	v_mfma_f32_16x16x32_bf16 v[90:93], v[190:193], v[214:217], v[90:93]
	v_mfma_f32_16x16x32_bf16 v[78:81], v[142:145], v[218:221], v[78:81]
	v_mfma_f32_16x16x32_bf16 v[78:81], v[182:185], v[222:225], v[78:81]
	v_mfma_f32_16x16x32_bf16 v[74:77], v[186:189], v[218:221], v[74:77]
	s_barrier
	v_mfma_f32_16x16x32_bf16 v[74:77], v[190:193], v[222:225], v[74:77]
	s_setprio 0
	s_add_i32 s51, 0, 0x1c000
	s_add_i32 s24, s39, s94
	v_add_u32_e32 v167, s51, v164
	v_lshl_add_u64 v[162:163], v[162:163], 0, s[12:13]
	s_mov_b32 m0, s24
	ds_read_b128 v[226:229], v167
	ds_read_b128 v[230:233], v167 offset:1024
	ds_read_b128 v[234:237], v167 offset:2048
	ds_read_b128 v[238:241], v167 offset:3072
	global_load_lds_dwordx4 v[162:163], off
	v_lshl_add_u64 v[162:163], v[168:169], 0, s[12:13]
	s_add_i32 m0, s24, 0x2000
	s_nop 0
	global_load_lds_dwordx4 v[162:163], off
	s_barrier
	s_waitcnt lgkmcnt(0)
	s_setprio 1
	s_waitcnt lgkmcnt(0)
	v_mfma_f32_16x16x32_bf16 v[118:121], v[226:229], v[194:197], v[118:121]
	v_mfma_f32_16x16x32_bf16 v[118:121], v[230:233], v[198:201], v[118:121]
	v_mfma_f32_16x16x32_bf16 v[114:117], v[234:237], v[194:197], v[114:117]
	v_mfma_f32_16x16x32_bf16 v[114:117], v[238:241], v[198:201], v[114:117]
	v_mfma_f32_16x16x32_bf16 v[102:105], v[226:229], v[202:205], v[102:105]
	v_mfma_f32_16x16x32_bf16 v[102:105], v[230:233], v[206:209], v[102:105]
	v_mfma_f32_16x16x32_bf16 v[98:101], v[234:237], v[202:205], v[98:101]
	v_mfma_f32_16x16x32_bf16 v[98:101], v[238:241], v[206:209], v[98:101]
	v_mfma_f32_16x16x32_bf16 v[86:89], v[226:229], v[210:213], v[86:89]
	v_mfma_f32_16x16x32_bf16 v[86:89], v[230:233], v[214:217], v[86:89]
	v_mfma_f32_16x16x32_bf16 v[82:85], v[234:237], v[210:213], v[82:85]
	v_mfma_f32_16x16x32_bf16 v[82:85], v[238:241], v[214:217], v[82:85]
	v_mfma_f32_16x16x32_bf16 v[70:73], v[226:229], v[218:221], v[70:73]
	v_mfma_f32_16x16x32_bf16 v[70:73], v[230:233], v[222:225], v[70:73]
	v_mfma_f32_16x16x32_bf16 v[66:69], v[234:237], v[218:221], v[66:69]
	s_barrier
	v_mfma_f32_16x16x32_bf16 v[66:69], v[238:241], v[222:225], v[66:69]
	s_setprio 0
	s_mov_b32 m0, s99
	v_lshl_add_u64 v[162:163], v[242:243], 0, s[12:13]
	ds_read_b128 v[194:197], v166 offset:49152
	ds_read_b128 v[198:201], v166 offset:50176
	ds_read_b128 v[202:205], v166 offset:51200
	ds_read_b128 v[206:209], v166 offset:52224
	ds_read_b128 v[210:213], v166 offset:53248
	ds_read_b128 v[214:217], v166 offset:54272
	ds_read_b128 v[218:221], v166 offset:55296
	ds_read_b128 v[222:225], v166 offset:56320
	global_load_lds_dwordx4 v[162:163], off
	v_lshl_add_u64 v[162:163], v[244:245], 0, s[12:13]
	s_mov_b32 m0, s82
	s_nop 0
	global_load_lds_dwordx4 v[162:163], off
	s_waitcnt vmcnt(8)
	s_barrier
	s_waitcnt lgkmcnt(0)
	s_setprio 1
	s_waitcnt lgkmcnt(0)
	v_mfma_f32_16x16x32_bf16 v[62:65], v[142:145], v[194:197], v[62:65]
	v_mfma_f32_16x16x32_bf16 v[62:65], v[182:185], v[198:201], v[62:65]
	v_mfma_f32_16x16x32_bf16 v[58:61], v[186:189], v[194:197], v[58:61]
	v_mfma_f32_16x16x32_bf16 v[58:61], v[190:193], v[198:201], v[58:61]
	v_mfma_f32_16x16x32_bf16 v[46:49], v[142:145], v[202:205], v[46:49]
	v_mfma_f32_16x16x32_bf16 v[46:49], v[182:185], v[206:209], v[46:49]
	v_mfma_f32_16x16x32_bf16 v[42:45], v[186:189], v[202:205], v[42:45]
	v_mfma_f32_16x16x32_bf16 v[42:45], v[190:193], v[206:209], v[42:45]
	v_mfma_f32_16x16x32_bf16 v[30:33], v[142:145], v[210:213], v[30:33]
	v_mfma_f32_16x16x32_bf16 v[30:33], v[182:185], v[214:217], v[30:33]
	v_mfma_f32_16x16x32_bf16 v[26:29], v[186:189], v[210:213], v[26:29]
	v_mfma_f32_16x16x32_bf16 v[26:29], v[190:193], v[214:217], v[26:29]
	v_mfma_f32_16x16x32_bf16 v[14:17], v[142:145], v[218:221], v[14:17]
	v_mfma_f32_16x16x32_bf16 v[14:17], v[182:185], v[222:225], v[14:17]
	v_mfma_f32_16x16x32_bf16 v[10:13], v[186:189], v[218:221], v[10:13]
	s_barrier
	v_mfma_f32_16x16x32_bf16 v[10:13], v[190:193], v[222:225], v[10:13]
	s_setprio 0
	s_add_u32 s24, s48, 0x40080
	s_addc_u32 s25, s49, 0
	s_add_i32 s39, s51, s94
	v_lshl_add_u64 v[142:143], s[24:25], 0, v[134:135]
	s_mov_b32 m0, s39
	s_nop 0
	global_load_lds_dwordx4 v[142:143], off
	v_lshl_add_u64 v[142:143], s[24:25], 0, v[130:131]
	s_add_i32 m0, s39, 0x2000
	s_nop 0
	global_load_lds_dwordx4 v[142:143], off
	s_waitcnt vmcnt(6)
	s_barrier
	s_setprio 1
	v_add_u32_e32 v249, 0x10000, v164
	v_mfma_f32_16x16x32_bf16 v[54:57], v[226:229], v[194:197], v[54:57]
	v_mfma_f32_16x16x32_bf16 v[54:57], v[230:233], v[198:201], v[54:57]
	ds_read_b128 v[142:145], v249
	v_mfma_f32_16x16x32_bf16 v[50:53], v[234:237], v[194:197], v[50:53]
	v_mfma_f32_16x16x32_bf16 v[50:53], v[238:241], v[198:201], v[50:53]
	v_mfma_f32_16x16x32_bf16 v[38:41], v[226:229], v[202:205], v[38:41]
	v_mfma_f32_16x16x32_bf16 v[38:41], v[230:233], v[206:209], v[38:41]
	ds_read_b128 v[182:185], v249 offset:1024
	v_mfma_f32_16x16x32_bf16 v[34:37], v[234:237], v[202:205], v[34:37]
	v_mfma_f32_16x16x32_bf16 v[34:37], v[238:241], v[206:209], v[34:37]
	v_mfma_f32_16x16x32_bf16 v[22:25], v[226:229], v[210:213], v[22:25]
	v_mfma_f32_16x16x32_bf16 v[22:25], v[230:233], v[214:217], v[22:25]
	ds_read_b128 v[186:189], v249 offset:2048
	v_mfma_f32_16x16x32_bf16 v[18:21], v[234:237], v[210:213], v[18:21]
	v_mfma_f32_16x16x32_bf16 v[18:21], v[238:241], v[214:217], v[18:21]
	v_mfma_f32_16x16x32_bf16 v[6:9], v[226:229], v[218:221], v[6:9]
	v_mfma_f32_16x16x32_bf16 v[6:9], v[230:233], v[222:225], v[6:9]
	ds_read_b128 v[190:193], v249 offset:3072
	v_mfma_f32_16x16x32_bf16 v[2:5], v[234:237], v[218:221], v[2:5]
	s_barrier
	v_mfma_f32_16x16x32_bf16 v[2:5], v[238:241], v[222:225], v[2:5]
	s_setprio 0
	s_add_i32 s38, s38, 2
	s_add_u32 s35, s35, 0x100
	s_addc_u32 s50, s50, 0
	s_add_u32 s0, s0, 0x100
	s_addc_u32 s1, s1, 0
	s_cmp_gt_u32 s38, 13
	s_cbranch_scc0 .LBB0_557
	s_waitcnt lgkmcnt(0)
	s_and_b64 vcc, exec, s[42:43]
	s_cbranch_vccz .LBB0_560
	s_barrier

; #define PG8_STAGE(bufoff, gbase, voff) do { _Pragma("unroll") for (int _i = 0; _i < 2; ++_i) \
;         __builtin_amdgcn_global_load_lds((const unsigned*)((const char*)(gbase) + (voff)[_i]), (LAS unsigned*)(lds + (bufoff) + ldsw + _i * 8192), 16, 0, 0); } while (0)
; #define PG8_LDA(dst, b, h) do { _Pragma("unroll") for (int m = 0; m < 4; ++m) _Pragma("unroll") for (int k = 0; k < 2; ++k) dst[m][k] = *(const LAS bf16x8*)(lds + PG8_SA(b, h) + aoff + m * 2048 + k * 1024); } while (0)
; #define PG8_LDB(dst, b, h) do { _Pragma("unroll") for (int n = 0; n < 2; ++n) _Pragma("unroll") for (int k = 0; k < 2; ++k) dst[n][k] = *(const LAS bf16x8*)(lds + PG8_SB(b, h) + boff + n * 2048 + k * 1024); } while (0)
; #define PG8_MMA(ai, bj, At, Bt) do { __builtin_amdgcn_s_setprio(1); _Pragma("unroll") for (int m = 0; m < 4; ++m) _Pragma("unroll") for (int n = 0; n < 2; ++n) _Pragma("unroll") for (int k = 0; k < 2; ++k) \
;         acc[ai][bj][m][n] = __builtin_amdgcn_mfma_f32_16x16x32_bf16(Bt[n][k], At[m][k], acc[ai][bj][m][n], 0, 0, 0); __builtin_amdgcn_s_setprio(0); } while (0)
; #define PG8_BAR __builtin_amdgcn_s_barrier()
; template <class Epi, class Sched>
; __device__ __forceinline__ void gemm_phase(LAS unsigned char* lds, const Gemm g, const Sched& S, const Epi& E) {
;     ...
;         const bool has_next = S.next(ui + 1, nxt);
;         const char* nA = has_next ? PG8_APANEL(nxt.pm) : cA; const char* nB = has_next ? (const char*)g.Bt + (size_t)nxt.pn * tstep : cB;
;         for (int t = 0; t < nt; t += 2) {
;             const bool last = (t == nt - 2);
;             const char* a1 = cA + (size_t)(t + 1) * kstep;
;             const char* a2 = last ? nA : cA + (size_t)(t + 2) * kstep; const char* b2 = last ? nB : cB + (size_t)(t + 2) * kstep;
;             const char* a3 = a2 + kstep; const char* b3 = b2 + kstep;
;             PG8_LDB(B0, 0, 0); PG8_SCHED; PG8_LDA(At, 0, 0); PG8_STAGE(PG8_SA(1, 1), a1 + hstep, voffA);
;             PG8_WAIT_L(8); PG8_BAR; PG8_WAIT_L(0); PG8_MMA(0, 0, At, B0); PG8_BAR; PG8_SCHED;
;     ...
; #pragma unroll
;         for (int a = 0; a < 2; ++a)
; #pragma unroll
;             for (int b = 0; b < 2; ++b)
; #pragma unroll
;                 for (int m = 0; m < 4; ++m)
; #pragma unroll
;                     for (int n = 0; n < 2; ++n) acc[a][b][m][n] = (f32x4){0.f, 0.f, 0.f, 0.f};
;         cur = nxt; cA = nA; cB = nB; ++ui;
.LBB0_626:
	s_ashr_i32 s43, s42, 31
	s_lshl_b64 s[24:25], s[42:43], 21
	s_add_u32 s60, s55, s24
	s_addc_u32 s61, s82, s25
	s_and_b64 s[0:1], s[0:1], exec
	s_cselect_b32 s43, s61, s49
	s_cselect_b32 s45, s60, s48
	s_add_u32 s35, s48, 0x100
	s_addc_u32 s50, s49, 0
	s_add_u32 s0, s76, 0x100080
	v_mov_b32_e32 v2, 0
	s_addc_u32 s1, s77, 0
	s_mov_b32 s98, -2
	v_mov_b32_e32 v3, v2
	v_mov_b32_e32 v4, v2
	v_mov_b32_e32 v5, v2
	v_mov_b32_e32 v6, v2
	v_mov_b32_e32 v7, v2
	v_mov_b32_e32 v8, v2
	v_mov_b32_e32 v9, v2
	v_mov_b32_e32 v10, v2
	v_mov_b32_e32 v11, v2
	v_mov_b32_e32 v12, v2
	v_mov_b32_e32 v13, v2
	v_mov_b32_e32 v18, v2
	v_mov_b32_e32 v19, v2
	v_mov_b32_e32 v20, v2
	v_mov_b32_e32 v21, v2
	v_mov_b32_e32 v26, v2
	v_mov_b32_e32 v27, v2
	v_mov_b32_e32 v28, v2
	v_mov_b32_e32 v29, v2
	v_mov_b32_e32 v34, v2
	v_mov_b32_e32 v35, v2
	v_mov_b32_e32 v36, v2
	v_mov_b32_e32 v37, v2
	v_mov_b32_e32 v42, v2
	v_mov_b32_e32 v43, v2
	v_mov_b32_e32 v44, v2
	v_mov_b32_e32 v45, v2
	v_mov_b32_e32 v50, v2
	v_mov_b32_e32 v51, v2
	v_mov_b32_e32 v52, v2
	v_mov_b32_e32 v53, v2
	v_mov_b32_e32 v14, v2
	v_mov_b32_e32 v15, v2
	v_mov_b32_e32 v16, v2
	v_mov_b32_e32 v17, v2
	v_mov_b32_e32 v22, v2
	v_mov_b32_e32 v23, v2
	v_mov_b32_e32 v24, v2
	v_mov_b32_e32 v25, v2
	v_mov_b32_e32 v30, v2
	v_mov_b32_e32 v31, v2
	v_mov_b32_e32 v32, v2
	v_mov_b32_e32 v33, v2
	v_mov_b32_e32 v38, v2
	v_mov_b32_e32 v39, v2
	v_mov_b32_e32 v40, v2
	v_mov_b32_e32 v41, v2
	v_mov_b32_e32 v46, v2
	v_mov_b32_e32 v47, v2
	v_mov_b32_e32 v48, v2
	v_mov_b32_e32 v49, v2
	v_mov_b32_e32 v54, v2
	v_mov_b32_e32 v55, v2
	v_mov_b32_e32 v56, v2
	v_mov_b32_e32 v57, v2
	v_mov_b32_e32 v58, v2
	v_mov_b32_e32 v59, v2
	v_mov_b32_e32 v60, v2
	v_mov_b32_e32 v61, v2
	v_mov_b32_e32 v62, v2
	v_mov_b32_e32 v63, v2
	v_mov_b32_e32 v64, v2
	v_mov_b32_e32 v65, v2
	v_mov_b32_e32 v66, v2
	v_mov_b32_e32 v67, v2
	v_mov_b32_e32 v68, v2
	v_mov_b32_e32 v69, v2
	v_mov_b32_e32 v70, v2
	v_mov_b32_e32 v71, v2
	v_mov_b32_e32 v72, v2
	v_mov_b32_e32 v73, v2
	v_mov_b32_e32 v74, v2
	v_mov_b32_e32 v75, v2
	v_mov_b32_e32 v76, v2
	v_mov_b32_e32 v77, v2
	v_mov_b32_e32 v82, v2
	v_mov_b32_e32 v83, v2
	v_mov_b32_e32 v84, v2
	v_mov_b32_e32 v85, v2
	v_mov_b32_e32 v90, v2
	v_mov_b32_e32 v91, v2
	v_mov_b32_e32 v92, v2
	v_mov_b32_e32 v93, v2
	v_mov_b32_e32 v98, v2
	v_mov_b32_e32 v99, v2
	v_mov_b32_e32 v100, v2
	v_mov_b32_e32 v101, v2
	v_mov_b32_e32 v106, v2
	v_mov_b32_e32 v107, v2
	v_mov_b32_e32 v108, v2
	v_mov_b32_e32 v109, v2
	v_mov_b32_e32 v114, v2
	v_mov_b32_e32 v115, v2
	v_mov_b32_e32 v116, v2
	v_mov_b32_e32 v117, v2
	v_mov_b32_e32 v78, v2
	v_mov_b32_e32 v79, v2
	v_mov_b32_e32 v80, v2
	v_mov_b32_e32 v81, v2
	v_mov_b32_e32 v86, v2
	v_mov_b32_e32 v87, v2
	v_mov_b32_e32 v88, v2
	v_mov_b32_e32 v89, v2
	v_mov_b32_e32 v94, v2
	v_mov_b32_e32 v95, v2
	v_mov_b32_e32 v96, v2
	v_mov_b32_e32 v97, v2
	v_mov_b32_e32 v102, v2
	v_mov_b32_e32 v103, v2
	v_mov_b32_e32 v104, v2
	v_mov_b32_e32 v105, v2
	v_mov_b32_e32 v110, v2
	v_mov_b32_e32 v111, v2
	v_mov_b32_e32 v112, v2
	v_mov_b32_e32 v113, v2
	v_mov_b32_e32 v118, v2
	v_mov_b32_e32 v119, v2
	v_mov_b32_e32 v120, v2
	v_mov_b32_e32 v121, v2
	v_mov_b32_e32 v122, v2
	v_mov_b32_e32 v123, v2
	v_mov_b32_e32 v124, v2
	v_mov_b32_e32 v125, v2
	v_mov_b32_e32 v126, v2
	v_mov_b32_e32 v127, v2
	v_mov_b32_e32 v128, v2
	v_mov_b32_e32 v129, v2
	v_add_u32_e32 v249, 0x10000, v144
	ds_read_b128 v[164:167], v249
	ds_read_b128 v[182:185], v249 offset:1024
	ds_read_b128 v[186:189], v249 offset:2048
	ds_read_b128 v[190:193], v249 offset:3072
.LBB0_627:
	s_add_u32 s24, s0, 0xfff00080
	s_addc_u32 s25, s1, -1
	s_add_i32 s51, 0, 0x10000
	v_add_u32_e32 v142, s51, v144
	s_cmp_eq_u32 s98, 60
	s_cselect_b32 s77, s47, s25
	s_cselect_b32 s76, s46, s24
	s_cselect_b32 s49, s43, s50
	s_cselect_b32 s48, s45, s35
	v_lshl_add_u64 v[142:143], s[0:1], 0, v[140:141]
	s_add_i32 m0, s86, 0xc000
	ds_read_b128 v[194:197], v162
	ds_read_b128 v[198:201], v162 offset:1024
	ds_read_b128 v[202:205], v162 offset:2048
	ds_read_b128 v[206:209], v162 offset:3072
	ds_read_b128 v[210:213], v162 offset:4096
	ds_read_b128 v[214:217], v162 offset:5120
	ds_read_b128 v[218:221], v162 offset:6144
	ds_read_b128 v[222:225], v162 offset:7168
	global_load_lds_dwordx4 v[142:143], off
	v_lshl_add_u64 v[142:143], s[0:1], 0, v[138:139]
	s_add_i32 m0, s86, 0xe000
	s_nop 0
	global_load_lds_dwordx4 v[142:143], off
	s_waitcnt lgkmcnt(8)
	s_barrier
	s_waitcnt lgkmcnt(0)
	s_setprio 1
	s_waitcnt lgkmcnt(0)
	v_mfma_f32_16x16x32_bf16 v[126:129], v[164:167], v[194:197], v[126:129]
	v_mfma_f32_16x16x32_bf16 v[126:129], v[182:185], v[198:201], v[126:129]
	v_mfma_f32_16x16x32_bf16 v[122:125], v[186:189], v[194:197], v[122:125]
	v_mfma_f32_16x16x32_bf16 v[122:125], v[190:193], v[198:201], v[122:125]
	v_mfma_f32_16x16x32_bf16 v[118:121], v[164:167], v[202:205], v[118:121]
	v_mfma_f32_16x16x32_bf16 v[118:121], v[182:185], v[206:209], v[118:121]
	v_mfma_f32_16x16x32_bf16 v[110:113], v[186:189], v[202:205], v[110:113]
	v_mfma_f32_16x16x32_bf16 v[110:113], v[190:193], v[206:209], v[110:113]
	v_mfma_f32_16x16x32_bf16 v[102:105], v[164:167], v[210:213], v[102:105]
	v_mfma_f32_16x16x32_bf16 v[102:105], v[182:185], v[214:217], v[102:105]
	v_mfma_f32_16x16x32_bf16 v[94:97], v[186:189], v[210:213], v[94:97]
	v_mfma_f32_16x16x32_bf16 v[94:97], v[190:193], v[214:217], v[94:97]
	v_mfma_f32_16x16x32_bf16 v[86:89], v[164:167], v[218:221], v[86:89]
	v_mfma_f32_16x16x32_bf16 v[86:89], v[182:185], v[222:225], v[86:89]
	v_mfma_f32_16x16x32_bf16 v[78:81], v[186:189], v[218:221], v[78:81]
	s_barrier
; #define PG8_STAGE(bufoff, gbase, voff) do { _Pragma("unroll") for (int _i = 0; _i < 2; ++_i) \
;         __builtin_amdgcn_global_load_lds((const unsigned*)((const char*)(gbase) + (voff)[_i]), (LAS unsigned*)(lds + (bufoff) + ldsw + _i * 8192), 16, 0, 0); } while (0)
; #define PG8_LDA(dst, b, h) do { _Pragma("unroll") for (int m = 0; m < 4; ++m) _Pragma("unroll") for (int k = 0; k < 2; ++k) dst[m][k] = *(const LAS bf16x8*)(lds + PG8_SA(b, h) + aoff + m * 2048 + k * 1024); } while (0)
; #define PG8_LDB(dst, b, h) do { _Pragma("unroll") for (int n = 0; n < 2; ++n) _Pragma("unroll") for (int k = 0; k < 2; ++k) dst[n][k] = *(const LAS bf16x8*)(lds + PG8_SB(b, h) + boff + n * 2048 + k * 1024); } while (0)
; #define PG8_MMA(ai, bj, At, Bt) do { __builtin_amdgcn_s_setprio(1); _Pragma("unroll") for (int m = 0; m < 4; ++m) _Pragma("unroll") for (int n = 0; n < 2; ++n) _Pragma("unroll") for (int k = 0; k < 2; ++k) \
;         acc[ai][bj][m][n] = __builtin_amdgcn_mfma_f32_16x16x32_bf16(Bt[n][k], At[m][k], acc[ai][bj][m][n], 0, 0, 0); __builtin_amdgcn_s_setprio(0); } while (0)
; #define PG8_WAIT_V(n) asm volatile("s_waitcnt vmcnt(" #n ")" ::: "memory")
; #define PG8_WAIT_L(n) asm volatile("s_waitcnt lgkmcnt(" #n ")" ::: "memory")
; #define PG8_BAR __builtin_amdgcn_s_barrier()
; #define PG8_SCHED __builtin_amdgcn_sched_barrier(0)
; template <class Epi, class Sched>
; __device__ __forceinline__ void gemm_phase(LAS unsigned char* lds, const Gemm g, const Sched& S, const Epi& E) {
;     ...
;             PG8_WAIT_L(8); PG8_BAR; PG8_WAIT_L(0); PG8_MMA(0, 0, At, B0); PG8_BAR; PG8_SCHED;
;             PG8_LDB(B1, 0, 1); PG8_STAGE(PG8_SB(0, 0), b2, voffB);
;             PG8_BAR; PG8_WAIT_L(0); PG8_MMA(0, 1, At, B1); PG8_BAR;
;             PG8_LDA(At, 0, 1); PG8_STAGE(PG8_SA(0, 0), a2, voffA);
;             PG8_BAR; PG8_WAIT_L(0); PG8_MMA(1, 0, At, B0); PG8_BAR; PG8_SCHED;
;             PG8_STAGE(PG8_SB(0, 1), b2 + hstep, voffB);
;             PG8_WAIT_V(6); PG8_BAR; PG8_MMA(1, 1, At, B1); PG8_BAR;
;             PG8_LDB(B0, 1, 0); PG8_SCHED; PG8_LDA(At, 1, 0); PG8_STAGE(PG8_SA(0, 1), a2 + hstep, voffA);
;             PG8_WAIT_L(8); PG8_BAR; PG8_WAIT_L(0); PG8_MMA(0, 0, At, B0); PG8_BAR; PG8_SCHED;
	v_mfma_f32_16x16x32_bf16 v[78:81], v[190:193], v[222:225], v[78:81]
	s_setprio 0
	s_add_i32 s99, 0, 0x14000
	v_add_u32_e32 v142, s99, v144
	s_add_i32 s24, s51, s83
	ds_read_b128 v[226:229], v142
	ds_read_b128 v[230:233], v142 offset:1024
	ds_read_b128 v[234:237], v142 offset:2048
	ds_read_b128 v[238:241], v142 offset:3072
	v_lshl_add_u64 v[142:143], s[48:49], 0, v[134:135]
	s_mov_b32 m0, s24
	v_lshl_add_u64 v[168:169], s[48:49], 0, v[130:131]
	global_load_lds_dwordx4 v[142:143], off
	s_add_i32 m0, s24, 0x2000
	s_nop 0
	global_load_lds_dwordx4 v[168:169], off
	s_barrier
	s_waitcnt lgkmcnt(0)
	s_setprio 1
	s_waitcnt lgkmcnt(0)
	v_mfma_f32_16x16x32_bf16 v[114:117], v[226:229], v[194:197], v[114:117]
	v_mfma_f32_16x16x32_bf16 v[114:117], v[230:233], v[198:201], v[114:117]
	v_mfma_f32_16x16x32_bf16 v[106:109], v[234:237], v[194:197], v[106:109]
	v_mfma_f32_16x16x32_bf16 v[106:109], v[238:241], v[198:201], v[106:109]
	v_mfma_f32_16x16x32_bf16 v[98:101], v[226:229], v[202:205], v[98:101]
	v_mfma_f32_16x16x32_bf16 v[98:101], v[230:233], v[206:209], v[98:101]
	v_mfma_f32_16x16x32_bf16 v[90:93], v[234:237], v[202:205], v[90:93]
	v_mfma_f32_16x16x32_bf16 v[90:93], v[238:241], v[206:209], v[90:93]
	v_mfma_f32_16x16x32_bf16 v[82:85], v[226:229], v[210:213], v[82:85]
	v_mfma_f32_16x16x32_bf16 v[82:85], v[230:233], v[214:217], v[82:85]
	v_mfma_f32_16x16x32_bf16 v[74:77], v[234:237], v[210:213], v[74:77]
	v_mfma_f32_16x16x32_bf16 v[74:77], v[238:241], v[214:217], v[74:77]
	v_mfma_f32_16x16x32_bf16 v[70:73], v[226:229], v[218:221], v[70:73]
	v_mfma_f32_16x16x32_bf16 v[70:73], v[230:233], v[222:225], v[70:73]
	v_mfma_f32_16x16x32_bf16 v[66:69], v[234:237], v[218:221], v[66:69]
	s_barrier
	v_mfma_f32_16x16x32_bf16 v[66:69], v[238:241], v[222:225], v[66:69]
	s_setprio 0
	s_mov_b32 m0, s86
	v_lshl_add_u64 v[242:243], s[76:77], 0, v[136:137]
	ds_read_b128 v[194:197], v162 offset:16384
	ds_read_b128 v[198:201], v162 offset:17408
	ds_read_b128 v[202:205], v162 offset:18432
	ds_read_b128 v[206:209], v162 offset:19456
	ds_read_b128 v[210:213], v162 offset:20480
	ds_read_b128 v[214:217], v162 offset:21504
	ds_read_b128 v[218:221], v162 offset:22528
	ds_read_b128 v[222:225], v162 offset:23552
	global_load_lds_dwordx4 v[242:243], off
	v_lshl_add_u64 v[244:245], s[76:77], 0, v[132:133]
	s_mov_b32 m0, s92
	s_nop 0
	global_load_lds_dwordx4 v[244:245], off
	s_waitcnt vmcnt(8)
	s_barrier
	s_waitcnt lgkmcnt(0)
	s_setprio 1
	s_waitcnt lgkmcnt(0)
	v_mfma_f32_16x16x32_bf16 v[62:65], v[164:167], v[194:197], v[62:65]
	v_mfma_f32_16x16x32_bf16 v[62:65], v[182:185], v[198:201], v[62:65]
	v_mfma_f32_16x16x32_bf16 v[58:61], v[186:189], v[194:197], v[58:61]
	v_mfma_f32_16x16x32_bf16 v[58:61], v[190:193], v[198:201], v[58:61]
	v_mfma_f32_16x16x32_bf16 v[54:57], v[164:167], v[202:205], v[54:57]
	v_mfma_f32_16x16x32_bf16 v[54:57], v[182:185], v[206:209], v[54:57]
	v_mfma_f32_16x16x32_bf16 v[46:49], v[186:189], v[202:205], v[46:49]
	v_mfma_f32_16x16x32_bf16 v[46:49], v[190:193], v[206:209], v[46:49]
	v_mfma_f32_16x16x32_bf16 v[38:41], v[164:167], v[210:213], v[38:41]
	v_mfma_f32_16x16x32_bf16 v[38:41], v[182:185], v[214:217], v[38:41]
	v_mfma_f32_16x16x32_bf16 v[30:33], v[186:189], v[210:213], v[30:33]
	v_mfma_f32_16x16x32_bf16 v[30:33], v[190:193], v[214:217], v[30:33]
	v_mfma_f32_16x16x32_bf16 v[22:25], v[164:167], v[218:221], v[22:25]
	v_mfma_f32_16x16x32_bf16 v[22:25], v[182:185], v[222:225], v[22:25]
	v_mfma_f32_16x16x32_bf16 v[14:17], v[186:189], v[218:221], v[14:17]
	s_barrier
	v_mfma_f32_16x16x32_bf16 v[14:17], v[190:193], v[222:225], v[14:17]
	s_setprio 0
	s_add_u32 s24, s48, 0x100000
	s_addc_u32 s25, s49, 0
	s_add_i32 s51, s99, s83
	v_lshl_add_u64 v[164:165], s[24:25], 0, v[134:135]
	s_mov_b32 m0, s51
	s_nop 0
	global_load_lds_dwordx4 v[164:165], off
	v_lshl_add_u64 v[164:165], s[24:25], 0, v[130:131]
	s_add_i32 m0, s51, 0x2000
	s_nop 0
	global_load_lds_dwordx4 v[164:165], off
	s_waitcnt vmcnt(6)
	s_barrier
	s_setprio 1
	v_add_u32_e32 v249, 0x18000, v144
	v_mfma_f32_16x16x32_bf16 v[50:53], v[226:229], v[194:197], v[50:53]
	v_mfma_f32_16x16x32_bf16 v[50:53], v[230:233], v[198:201], v[50:53]
	ds_read_b128 v[164:167], v249
	v_mfma_f32_16x16x32_bf16 v[42:45], v[234:237], v[194:197], v[42:45]
	v_mfma_f32_16x16x32_bf16 v[42:45], v[238:241], v[198:201], v[42:45]
	v_mfma_f32_16x16x32_bf16 v[34:37], v[226:229], v[202:205], v[34:37]
	v_mfma_f32_16x16x32_bf16 v[34:37], v[230:233], v[206:209], v[34:37]
	ds_read_b128 v[182:185], v249 offset:1024
	v_mfma_f32_16x16x32_bf16 v[26:29], v[234:237], v[202:205], v[26:29]
	v_mfma_f32_16x16x32_bf16 v[26:29], v[238:241], v[206:209], v[26:29]
	v_mfma_f32_16x16x32_bf16 v[18:21], v[226:229], v[210:213], v[18:21]
	v_mfma_f32_16x16x32_bf16 v[18:21], v[230:233], v[214:217], v[18:21]
	ds_read_b128 v[186:189], v249 offset:2048
	v_mfma_f32_16x16x32_bf16 v[10:13], v[234:237], v[210:213], v[10:13]
	v_mfma_f32_16x16x32_bf16 v[10:13], v[238:241], v[214:217], v[10:13]
	v_mfma_f32_16x16x32_bf16 v[6:9], v[226:229], v[218:221], v[6:9]
	v_mfma_f32_16x16x32_bf16 v[6:9], v[230:233], v[222:225], v[6:9]
	ds_read_b128 v[190:193], v249 offset:3072
	v_mfma_f32_16x16x32_bf16 v[2:5], v[234:237], v[218:221], v[2:5]
	s_barrier
	v_mfma_f32_16x16x32_bf16 v[2:5], v[238:241], v[222:225], v[2:5]
	s_setprio 0
	s_add_i32 s51, 0, 0x18000
	v_add_u32_e32 v163, s51, v144
	s_add_u32 s24, s76, 0x100000
	s_addc_u32 s25, s77, 0
	s_mov_b32 m0, s93
	v_lshl_add_u64 v[226:227], s[24:25], 0, v[136:137]
	ds_read_b128 v[194:197], v162 offset:32768
	ds_read_b128 v[198:201], v162 offset:33792
	ds_read_b128 v[202:205], v162 offset:34816
	ds_read_b128 v[206:209], v162 offset:35840
	ds_read_b128 v[210:213], v162 offset:36864
	ds_read_b128 v[214:217], v162 offset:37888
	ds_read_b128 v[218:221], v162 offset:38912
	ds_read_b128 v[222:225], v162 offset:39936
	global_load_lds_dwordx4 v[226:227], off
	v_lshl_add_u64 v[226:227], s[24:25], 0, v[132:133]
	s_mov_b32 m0, s94
	s_nop 0
	global_load_lds_dwordx4 v[226:227], off
	s_waitcnt lgkmcnt(8)
	s_barrier
; #define PG8_STAGE(bufoff, gbase, voff) do { _Pragma("unroll") for (int _i = 0; _i < 2; ++_i) \
;         __builtin_amdgcn_global_load_lds((const unsigned*)((const char*)(gbase) + (voff)[_i]), (LAS unsigned*)(lds + (bufoff) + ldsw + _i * 8192), 16, 0, 0); } while (0)
; #define PG8_LDA(dst, b, h) do { _Pragma("unroll") for (int m = 0; m < 4; ++m) _Pragma("unroll") for (int k = 0; k < 2; ++k) dst[m][k] = *(const LAS bf16x8*)(lds + PG8_SA(b, h) + aoff + m * 2048 + k * 1024); } while (0)
; #define PG8_LDB(dst, b, h) do { _Pragma("unroll") for (int n = 0; n < 2; ++n) _Pragma("unroll") for (int k = 0; k < 2; ++k) dst[n][k] = *(const LAS bf16x8*)(lds + PG8_SB(b, h) + boff + n * 2048 + k * 1024); } while (0)
; #define PG8_MMA(ai, bj, At, Bt) do { __builtin_amdgcn_s_setprio(1); _Pragma("unroll") for (int m = 0; m < 4; ++m) _Pragma("unroll") for (int n = 0; n < 2; ++n) _Pragma("unroll") for (int k = 0; k < 2; ++k) \
;         acc[ai][bj][m][n] = __builtin_amdgcn_mfma_f32_16x16x32_bf16(Bt[n][k], At[m][k], acc[ai][bj][m][n], 0, 0, 0); __builtin_amdgcn_s_setprio(0); } while (0)
; #define PG8_WAIT_V(n) asm volatile("s_waitcnt vmcnt(" #n ")" ::: "memory")
; #define PG8_WAIT_L(n) asm volatile("s_waitcnt lgkmcnt(" #n ")" ::: "memory")
; #define PG8_BAR __builtin_amdgcn_s_barrier()
; #define PG8_SCHED __builtin_amdgcn_sched_barrier(0)
; template <class Epi, class Sched>
; __device__ __forceinline__ void gemm_phase(LAS unsigned char* lds, const Gemm g, const Sched& S, const Epi& E) {
;     ...
;             PG8_WAIT_L(8); PG8_BAR; PG8_WAIT_L(0); PG8_MMA(0, 0, At, B0); PG8_BAR; PG8_SCHED;
;             PG8_LDB(B1, 1, 1); PG8_STAGE(PG8_SB(1, 0), b3, voffB);
;             PG8_BAR; PG8_WAIT_L(0); PG8_MMA(0, 1, At, B1); PG8_BAR;
;             PG8_LDA(At, 1, 1); PG8_STAGE(PG8_SA(1, 0), a3, voffA);
;             PG8_BAR; PG8_WAIT_L(0); PG8_MMA(1, 0, At, B0); PG8_BAR; PG8_SCHED;
;             PG8_STAGE(PG8_SB(1, 1), b3 + hstep, voffB);
;             PG8_WAIT_V(6); PG8_BAR; PG8_MMA(1, 1, At, B1); PG8_BAR;
;         }
;         if (wr == 0) PG8_BAR;
	s_waitcnt lgkmcnt(0)
	s_setprio 1
	s_waitcnt lgkmcnt(0)
	v_mfma_f32_16x16x32_bf16 v[126:129], v[164:167], v[194:197], v[126:129]
	v_mfma_f32_16x16x32_bf16 v[126:129], v[182:185], v[198:201], v[126:129]
	v_mfma_f32_16x16x32_bf16 v[122:125], v[186:189], v[194:197], v[122:125]
	v_mfma_f32_16x16x32_bf16 v[122:125], v[190:193], v[198:201], v[122:125]
	v_mfma_f32_16x16x32_bf16 v[118:121], v[164:167], v[202:205], v[118:121]
	v_mfma_f32_16x16x32_bf16 v[118:121], v[182:185], v[206:209], v[118:121]
	v_mfma_f32_16x16x32_bf16 v[110:113], v[186:189], v[202:205], v[110:113]
	v_mfma_f32_16x16x32_bf16 v[110:113], v[190:193], v[206:209], v[110:113]
	v_mfma_f32_16x16x32_bf16 v[102:105], v[164:167], v[210:213], v[102:105]
	v_mfma_f32_16x16x32_bf16 v[102:105], v[182:185], v[214:217], v[102:105]
	v_mfma_f32_16x16x32_bf16 v[94:97], v[186:189], v[210:213], v[94:97]
	v_mfma_f32_16x16x32_bf16 v[94:97], v[190:193], v[214:217], v[94:97]
	v_mfma_f32_16x16x32_bf16 v[86:89], v[164:167], v[218:221], v[86:89]
	v_mfma_f32_16x16x32_bf16 v[86:89], v[182:185], v[222:225], v[86:89]
	v_mfma_f32_16x16x32_bf16 v[78:81], v[186:189], v[218:221], v[78:81]
	s_barrier
	v_mfma_f32_16x16x32_bf16 v[78:81], v[190:193], v[222:225], v[78:81]
	s_setprio 0
	s_add_i32 s76, 0, 0x1c000
	s_add_i32 s24, s51, s83
	v_add_u32_e32 v163, s76, v144
	v_lshl_add_u64 v[142:143], v[142:143], 0, s[12:13]
	s_mov_b32 m0, s24
	ds_read_b128 v[226:229], v163
	ds_read_b128 v[230:233], v163 offset:1024
	ds_read_b128 v[234:237], v163 offset:2048
	ds_read_b128 v[238:241], v163 offset:3072
	global_load_lds_dwordx4 v[142:143], off
	v_lshl_add_u64 v[142:143], v[168:169], 0, s[12:13]
	s_add_i32 m0, s24, 0x2000
	s_nop 0
	global_load_lds_dwordx4 v[142:143], off
	s_barrier
	s_waitcnt lgkmcnt(0)
	s_setprio 1
	s_waitcnt lgkmcnt(0)
	v_mfma_f32_16x16x32_bf16 v[114:117], v[226:229], v[194:197], v[114:117]
	v_mfma_f32_16x16x32_bf16 v[114:117], v[230:233], v[198:201], v[114:117]
	v_mfma_f32_16x16x32_bf16 v[106:109], v[234:237], v[194:197], v[106:109]
	v_mfma_f32_16x16x32_bf16 v[106:109], v[238:241], v[198:201], v[106:109]
	v_mfma_f32_16x16x32_bf16 v[98:101], v[226:229], v[202:205], v[98:101]
	v_mfma_f32_16x16x32_bf16 v[98:101], v[230:233], v[206:209], v[98:101]
	v_mfma_f32_16x16x32_bf16 v[90:93], v[234:237], v[202:205], v[90:93]
	v_mfma_f32_16x16x32_bf16 v[90:93], v[238:241], v[206:209], v[90:93]
	v_mfma_f32_16x16x32_bf16 v[82:85], v[226:229], v[210:213], v[82:85]
	v_mfma_f32_16x16x32_bf16 v[82:85], v[230:233], v[214:217], v[82:85]
	v_mfma_f32_16x16x32_bf16 v[74:77], v[234:237], v[210:213], v[74:77]
	v_mfma_f32_16x16x32_bf16 v[74:77], v[238:241], v[214:217], v[74:77]
	v_mfma_f32_16x16x32_bf16 v[70:73], v[226:229], v[218:221], v[70:73]
	v_mfma_f32_16x16x32_bf16 v[70:73], v[230:233], v[222:225], v[70:73]
	v_mfma_f32_16x16x32_bf16 v[66:69], v[234:237], v[218:221], v[66:69]
	s_barrier
	v_mfma_f32_16x16x32_bf16 v[66:69], v[238:241], v[222:225], v[66:69]
	s_setprio 0
	s_mov_b32 m0, s95
	v_lshl_add_u64 v[142:143], v[242:243], 0, s[12:13]
	ds_read_b128 v[194:197], v162 offset:49152
	ds_read_b128 v[198:201], v162 offset:50176
	ds_read_b128 v[202:205], v162 offset:51200
	ds_read_b128 v[206:209], v162 offset:52224
	ds_read_b128 v[210:213], v162 offset:53248
	ds_read_b128 v[214:217], v162 offset:54272
	ds_read_b128 v[218:221], v162 offset:55296
	ds_read_b128 v[222:225], v162 offset:56320
	global_load_lds_dwordx4 v[142:143], off
	v_lshl_add_u64 v[142:143], v[244:245], 0, s[12:13]
	s_mov_b32 m0, s96
	s_nop 0
	global_load_lds_dwordx4 v[142:143], off
	s_waitcnt vmcnt(8)
	s_barrier
	s_waitcnt lgkmcnt(0)
	s_setprio 1
	s_waitcnt lgkmcnt(0)
	v_mfma_f32_16x16x32_bf16 v[62:65], v[164:167], v[194:197], v[62:65]
	v_mfma_f32_16x16x32_bf16 v[62:65], v[182:185], v[198:201], v[62:65]
	v_mfma_f32_16x16x32_bf16 v[58:61], v[186:189], v[194:197], v[58:61]
	v_mfma_f32_16x16x32_bf16 v[58:61], v[190:193], v[198:201], v[58:61]
	v_mfma_f32_16x16x32_bf16 v[54:57], v[164:167], v[202:205], v[54:57]
	v_mfma_f32_16x16x32_bf16 v[54:57], v[182:185], v[206:209], v[54:57]
	v_mfma_f32_16x16x32_bf16 v[46:49], v[186:189], v[202:205], v[46:49]
	v_mfma_f32_16x16x32_bf16 v[46:49], v[190:193], v[206:209], v[46:49]
	v_mfma_f32_16x16x32_bf16 v[38:41], v[164:167], v[210:213], v[38:41]
	v_mfma_f32_16x16x32_bf16 v[38:41], v[182:185], v[214:217], v[38:41]
	v_mfma_f32_16x16x32_bf16 v[30:33], v[186:189], v[210:213], v[30:33]
	v_mfma_f32_16x16x32_bf16 v[30:33], v[190:193], v[214:217], v[30:33]
	v_mfma_f32_16x16x32_bf16 v[22:25], v[164:167], v[218:221], v[22:25]
	v_mfma_f32_16x16x32_bf16 v[22:25], v[182:185], v[222:225], v[22:25]
	v_mfma_f32_16x16x32_bf16 v[14:17], v[186:189], v[218:221], v[14:17]
	s_barrier
	v_mfma_f32_16x16x32_bf16 v[14:17], v[190:193], v[222:225], v[14:17]
	s_setprio 0
	s_add_u32 s24, s48, 0x100080
	s_addc_u32 s25, s49, 0
	s_add_i32 s48, s76, s83
	v_lshl_add_u64 v[142:143], s[24:25], 0, v[134:135]
	s_mov_b32 m0, s48
	s_nop 0
	global_load_lds_dwordx4 v[142:143], off
	v_lshl_add_u64 v[142:143], s[24:25], 0, v[130:131]
	s_add_i32 m0, s48, 0x2000
	s_nop 0
	global_load_lds_dwordx4 v[142:143], off
	s_waitcnt vmcnt(6)
	s_barrier
	s_setprio 1
	v_add_u32_e32 v249, 0x10000, v144
	v_mfma_f32_16x16x32_bf16 v[50:53], v[226:229], v[194:197], v[50:53]
	v_mfma_f32_16x16x32_bf16 v[50:53], v[230:233], v[198:201], v[50:53]
	ds_read_b128 v[164:167], v249
	v_mfma_f32_16x16x32_bf16 v[42:45], v[234:237], v[194:197], v[42:45]
	v_mfma_f32_16x16x32_bf16 v[42:45], v[238:241], v[198:201], v[42:45]
	v_mfma_f32_16x16x32_bf16 v[34:37], v[226:229], v[202:205], v[34:37]
	v_mfma_f32_16x16x32_bf16 v[34:37], v[230:233], v[206:209], v[34:37]
	ds_read_b128 v[182:185], v249 offset:1024
	v_mfma_f32_16x16x32_bf16 v[26:29], v[234:237], v[202:205], v[26:29]
	v_mfma_f32_16x16x32_bf16 v[26:29], v[238:241], v[206:209], v[26:29]
	v_mfma_f32_16x16x32_bf16 v[18:21], v[226:229], v[210:213], v[18:21]
	v_mfma_f32_16x16x32_bf16 v[18:21], v[230:233], v[214:217], v[18:21]
	ds_read_b128 v[186:189], v249 offset:2048
	v_mfma_f32_16x16x32_bf16 v[10:13], v[234:237], v[210:213], v[10:13]
	v_mfma_f32_16x16x32_bf16 v[10:13], v[238:241], v[214:217], v[10:13]
	v_mfma_f32_16x16x32_bf16 v[6:9], v[226:229], v[218:221], v[6:9]
	v_mfma_f32_16x16x32_bf16 v[6:9], v[230:233], v[222:225], v[6:9]
	ds_read_b128 v[190:193], v249 offset:3072
	v_mfma_f32_16x16x32_bf16 v[2:5], v[234:237], v[218:221], v[2:5]
	s_barrier
	v_mfma_f32_16x16x32_bf16 v[2:5], v[238:241], v[222:225], v[2:5]
	s_setprio 0
	s_add_i32 s98, s98, 2
	s_add_u32 s35, s35, 0x100
	s_addc_u32 s50, s50, 0
	s_add_u32 s0, s0, 0x100
	s_addc_u32 s1, s1, 0
	s_cmp_gt_u32 s98, 61
	s_cbranch_scc0 .LBB0_627
	s_waitcnt lgkmcnt(0)
	s_and_b64 vcc, exec, s[40:41]
	s_cbranch_vccz .LBB0_630
	s_barrier
